# weight-image transposes rewritten: barrier-free wave-private 64x64 tiles, 16 loads in flight, 128-B store runs; LN loads de-serialised
# speedup vs baseline: 1.0562x; 1.0048x over previous
; #define LAS __attribute__((address_space(3)))
; __device__ __forceinline__ unsigned pk_bf16(float lo, float hi) { const f32x2_t f = {lo, hi}; return __builtin_bit_cast(unsigned, __builtin_convertvector(f, bf16x2_t)); }
; __device__ __forceinline__ int otid() { int t = threadIdx.x; asm volatile("" : "+v"(t)); return t; }
; __device__ __forceinline__ int obid() { int b = blockIdx.x; asm volatile("" : "+s"(b)); return b; }
; __device__ __forceinline__ void wtrans(const float* __restrict__ src, int K, int N, bf16_t* __restrict__ dst, int ldd, int mode, LAS float* tile) {
;     const int tid = otid(), tn = N >> 6, nt = (K >> 6) * tn;
;     for (int t = obid(); t < nt; t += gridDim.x) {
;         const int k0 = (t / tn) << 6, c0 = (t % tn) << 6;
;         {
; #pragma unroll
;           for (int i = 0; i < 2; ++i) { const int e = tid + 512 * i, kl = e >> 4, c4 = (e & 15) * 4;
;               const f32x4 v4 = *(const f32x4*)(src + (size_t)(k0 + kl) * N + c0 + c4);
;               tile[kl * 65 + c4] = v4[0]; tile[kl * 65 + c4 + 1] = v4[1]; tile[kl * 65 + c4 + 2] = v4[2]; tile[kl * 65 + c4 + 3] = v4[3]; } }
;         __syncthreads();
;         { const int kp = tid & 31, cl0 = tid >> 5;
; #pragma unroll
;           for (int i = 0; i < 4; ++i) { const int cl = cl0 + 16 * i, c = c0 + cl; const int R = mode ? gu_row(c) : c;
;               *(unsigned*)(dst + (size_t)R * ldd + k0 + 2 * kp) = pk_bf16(tile[(2 * kp) * 65 + cl], tile[(2 * kp + 1) * 65 + cl]); } }
;         __syncthreads();
;     }
; }
; __device__ __forceinline__ void phase_wprep(const Params& p, int l, LAS float* tile) {
;     bf16_t* WB = (bf16_t*)(p.ws + WS_WB);
;     wtrans(p.in[1] + (size_t)(l * 2 + 0) * 1024 * 5632, 1024, 5632, WB + WB_GU0, 1024, 1, tile);
;     wtrans(p.in[1] + (size_t)(l * 2 + 1) * 1024 * 5632, 1024, 5632, WB + WB_GU1, 1024, 1, tile);
;     wtrans(p.in[2] + (size_t)(l * 2 + 0) * 2816 * 1024, 2816, 1024, WB + WB_D0, 2816, 0, tile);
;     wtrans(p.in[2] + (size_t)(l * 2 + 1) * 2816 * 1024, 2816, 1024, WB + WB_D1, 2816, 0, tile);
;     wtrans(p.in[5] + (size_t)l * 1024 * 4608, 1024, 4608, WB + WB_IN, 1024, 0, tile);
;     wtrans(p.in[23] + (size_t)l * 512 * 1024, 512, 1024, WB + WB_BA, 512, 0, tile);
;     wtrans(p.in[24] + (size_t)l * 512 * 1024, 512, 1024, WB + WB_BB, 512, 0, tile);
;     wtrans(p.in[25] + (size_t)l * 1024 * 1024, 1024, 1024, WB + WB_O, 1024, 0, tile);
.Lwpa_entry:
	v_and_b32_e32 v1, 63, v183
	v_lshrrev_b32_e32 v15, 6, v183
	s_nop 0
	v_readfirstlane_b32 s87, v15
	s_lshl_b32 s13, s2, 3
	s_add_u32 s13, s13, s87
	s_mul_i32 s87, s87, 8448
	v_lshrrev_b32_e32 v10, 4, v1
	v_and_b32_e32 v11, 15, v1
	v_mul_u32_u24_e32 v2, 528, v11
	v_lshl_add_u32 v2, v10, 2, v2
	v_add_u32_e32 v2, s87, v2
	v_lshlrev_b32_e32 v10, 1, v10
	v_lshlrev_b32_e32 v11, 4, v11
	v_lshrrev_b32_e32 v13, 5, v1
	v_and_b32_e32 v14, 31, v1
	v_lshlrev_b32_e32 v14, 2, v14
	v_mul_u32_u24_e32 v4, 132, v13
	v_add_u32_e32 v4, v4, v14
	v_add_u32_e32 v4, s87, v4
	v_readlane_b32 s0, v252, 0
	v_readlane_b32 s1, v252, 1
	s_sub_u32 s0, s0, 0xe0
	s_subb_u32 s1, s1, 0
.Lwpa_tile:
	s_cmp_ge_u32 s13, 5888
	s_cbranch_scc1 .Lwpa_done
	s_cmp_lt_u32 s13, 1408
	s_cbranch_scc1 .Lwpa_m0
	s_cmp_lt_u32 s13, 2816
	s_cbranch_scc1 .Lwpa_m1
	s_cmp_lt_u32 s13, 3520
	s_cbranch_scc1 .Lwpa_m2
	s_cmp_lt_u32 s13, 4224
	s_cbranch_scc1 .Lwpa_m3
	s_cmp_lt_u32 s13, 5376
	s_cbranch_scc1 .Lwpa_m4
	s_cmp_lt_u32 s13, 5504
	s_cbranch_scc1 .Lwpa_m5
	s_cmp_lt_u32 s13, 5632
	s_cbranch_scc1 .Lwpa_m6
	s_branch .Lwpa_m7
.Lwpa_m0:
	s_sub_u32 s25, s13, 0
	s_mul_hi_u32 s32, s25, 0x2e8ba2f
	s_mul_i32 s87, s32, 88
	s_sub_u32 s50, s25, s87
	s_load_dwordx2 s[14:15], s[0:1], 0x8
	s_waitcnt lgkmcnt(0)
	s_mul_i32 s87, s32, 1441792
	s_lshl_b32 s88, s50, 8
	s_add_u32 s87, s87, s88
	s_add_u32 s14, s14, s87
	s_addc_u32 s15, s15, 0
	s_mov_b32 s52, 22528
	s_mov_b32 s53, 180224
	s_mov_b32 s80, 2048
	s_cmp_ge_u32 s50, 44
	s_cselect_b32 s87, 1, 0
	s_mul_i32 s88, s87, 44
	s_sub_u32 s88, s50, s88
	s_lshl_b32 s86, s87, 4
	s_and_b32 s87, s88, 1
	s_lshl_b32 s87, s87, 6
	s_add_u32 s86, s86, s87
	s_lshr_b32 s88, s88, 1
	s_lshl_b32 s88, s88, 8
	s_add_u32 s86, s86, s88
	s_mul_i32 s87, s86, 2048
	s_lshl_b32 s88, s32, 7
	s_add_u32 s87, s87, s88
	s_add_u32 s87, s87, 0x0
	s_add_u32 s36, s70, s87
	s_addc_u32 s37, s71, 0
	s_branch .Lwpa_body1
.Lwpa_m1:
	s_sub_u32 s25, s13, 1408
	s_mul_hi_u32 s32, s25, 0x2e8ba2f
	s_mul_i32 s87, s32, 88
	s_sub_u32 s50, s25, s87
	s_load_dwordx2 s[14:15], s[0:1], 0x8
	s_waitcnt lgkmcnt(0)
	s_mul_i32 s87, s32, 1441792
	s_lshl_b32 s88, s50, 8
	s_add_u32 s87, s87, s88
	s_add_u32 s14, s14, 0x1600000
	s_addc_u32 s15, s15, 0
	s_add_u32 s14, s14, s87
	s_addc_u32 s15, s15, 0
	s_mov_b32 s52, 22528
	s_mov_b32 s53, 180224
	s_mov_b32 s80, 2048
	s_cmp_ge_u32 s50, 44
	s_cselect_b32 s87, 1, 0
	s_mul_i32 s88, s87, 44
	s_sub_u32 s88, s50, s88
	s_lshl_b32 s86, s87, 4
	s_and_b32 s87, s88, 1
	s_lshl_b32 s87, s87, 6
	s_add_u32 s86, s86, s87
	s_lshr_b32 s88, s88, 1
	s_lshl_b32 s88, s88, 8
	s_add_u32 s86, s86, s88
	s_mul_i32 s87, s86, 2048
	s_lshl_b32 s88, s32, 7
	s_add_u32 s87, s87, s88
	s_add_u32 s87, s87, 0xb00000
	s_add_u32 s36, s70, s87
	s_addc_u32 s37, s71, 0
	s_branch .Lwpa_body1
.Lwpa_m2:
	s_sub_u32 s25, s13, 2816
	s_lshr_b32 s32, s25, 4
	s_and_b32 s50, s25, 15
	s_load_dwordx2 s[14:15], s[0:1], 0x10
	s_waitcnt lgkmcnt(0)
	s_mul_i32 s87, s32, 262144
	s_lshl_b32 s88, s50, 8
	s_add_u32 s87, s87, s88
	s_add_u32 s14, s14, s87
	s_addc_u32 s15, s15, 0
	s_mov_b32 s52, 4096
	s_mov_b32 s53, 32768
	s_mov_b32 s80, 5632
	s_lshl_b32 s86, s50, 6
	s_mul_i32 s87, s86, 5632
	s_lshl_b32 s88, s32, 7
	s_add_u32 s87, s87, s88
	s_add_u32 s87, s87, 0x1600000
	s_add_u32 s36, s70, s87
	s_addc_u32 s37, s71, 0
	s_branch .Lwpa_body0
.Lwpa_m3:
	s_sub_u32 s25, s13, 3520
	s_lshr_b32 s32, s25, 4
	s_and_b32 s50, s25, 15
	s_load_dwordx2 s[14:15], s[0:1], 0x10
	s_waitcnt lgkmcnt(0)
	s_mul_i32 s87, s32, 262144
	s_lshl_b32 s88, s50, 8
	s_add_u32 s87, s87, s88
	s_add_u32 s14, s14, 0xb00000
	s_addc_u32 s15, s15, 0
	s_add_u32 s14, s14, s87
	s_addc_u32 s15, s15, 0
	s_mov_b32 s52, 4096
	s_mov_b32 s53, 32768
	s_mov_b32 s80, 5632
	s_lshl_b32 s86, s50, 6
	s_mul_i32 s87, s86, 5632
	s_lshl_b32 s88, s32, 7
	s_add_u32 s87, s87, s88
	s_add_u32 s87, s87, 0x1b80000
	s_add_u32 s36, s70, s87
	s_addc_u32 s37, s71, 0
	s_branch .Lwpa_body0
.Lwpa_m4:
	s_sub_u32 s25, s13, 4224
	s_mul_hi_u32 s32, s25, 0x38e38e4
	s_mul_i32 s87, s32, 72
	s_sub_u32 s50, s25, s87
	s_load_dwordx2 s[14:15], s[0:1], 0x28
	s_waitcnt lgkmcnt(0)
	s_mul_i32 s87, s32, 1179648
	s_lshl_b32 s88, s50, 8
	s_add_u32 s87, s87, s88
	s_add_u32 s14, s14, s87
	s_addc_u32 s15, s15, 0
	s_mov_b32 s52, 18432
	s_mov_b32 s53, 147456
	s_mov_b32 s80, 2048
	s_lshl_b32 s86, s50, 6
	s_mul_i32 s87, s86, 2048
	s_lshl_b32 s88, s32, 7
	s_add_u32 s87, s87, s88
	s_add_u32 s87, s87, 0x2100000
	s_add_u32 s36, s70, s87
	s_addc_u32 s37, s71, 0
	s_branch .Lwpa_body0
.Lwpa_m5:
	s_sub_u32 s25, s13, 5376
	s_lshr_b32 s32, s25, 4
	s_and_b32 s50, s25, 15
	s_load_dwordx2 s[14:15], s[0:1], 0xb8
	s_waitcnt lgkmcnt(0)
	s_mul_i32 s87, s32, 262144
	s_lshl_b32 s88, s50, 8
	s_add_u32 s87, s87, s88
	s_add_u32 s14, s14, s87
	s_addc_u32 s15, s15, 0
	s_mov_b32 s52, 4096
	s_mov_b32 s53, 32768
	s_mov_b32 s80, 1024
	s_lshl_b32 s86, s50, 6
	s_mul_i32 s87, s86, 1024
	s_lshl_b32 s88, s32, 7
	s_add_u32 s87, s87, s88
	s_add_u32 s87, s87, 0x2a00000
	s_add_u32 s36, s70, s87
	s_addc_u32 s37, s71, 0
	s_branch .Lwpa_body0
.Lwpa_m6:
	s_sub_u32 s25, s13, 5504
	s_lshr_b32 s32, s25, 4
	s_and_b32 s50, s25, 15
	s_mov_b64 s[14:15], s[64:65]
	s_mul_i32 s87, s32, 262144
	s_lshl_b32 s88, s50, 8
	s_add_u32 s87, s87, s88
	s_add_u32 s14, s14, s87
	s_addc_u32 s15, s15, 0
	s_mov_b32 s52, 4096
	s_mov_b32 s53, 32768
	s_mov_b32 s80, 1024
	s_lshl_b32 s86, s50, 6
	s_mul_i32 s87, s86, 1024
	s_lshl_b32 s88, s32, 7
	s_add_u32 s87, s87, s88
	s_add_u32 s87, s87, 0x2b00000
	s_add_u32 s36, s70, s87
	s_addc_u32 s37, s71, 0
	s_branch .Lwpa_body0
; __device__ __forceinline__ unsigned pk_bf16(float lo, float hi) { const f32x2_t f = {lo, hi}; return __builtin_bit_cast(unsigned, __builtin_convertvector(f, bf16x2_t)); }
; __device__ __forceinline__ int obid() { int b = blockIdx.x; asm volatile("" : "+s"(b)); return b; }
; __device__ __forceinline__ void wtrans(const float* __restrict__ src, int K, int N, bf16_t* __restrict__ dst, int ldd, int mode, LAS float* tile) {
;     ...
;     for (int t = obid(); t < nt; t += gridDim.x) {
;         const int k0 = (t / tn) << 6, c0 = (t % tn) << 6;
;         {
; #pragma unroll
;           for (int i = 0; i < 2; ++i) { const int e = tid + 512 * i, kl = e >> 4, c4 = (e & 15) * 4;
;               const f32x4 v4 = *(const f32x4*)(src + (size_t)(k0 + kl) * N + c0 + c4);
;               tile[kl * 65 + c4] = v4[0]; tile[kl * 65 + c4 + 1] = v4[1]; tile[kl * 65 + c4 + 2] = v4[2]; tile[kl * 65 + c4 + 3] = v4[3]; } }
;         __syncthreads();
;         { const int kp = tid & 31, cl0 = tid >> 5;
; #pragma unroll
;           for (int i = 0; i < 4; ++i) { const int cl = cl0 + 16 * i, c = c0 + cl; const int R = mode ? gu_row(c) : c;
;               *(unsigned*)(dst + (size_t)R * ldd + k0 + 2 * kp) = pk_bf16(tile[(2 * kp) * 65 + cl], tile[(2 * kp + 1) * 65 + cl]); } }
; __device__ __forceinline__ void phase_wprep(const Params& p, int l, LAS float* tile) {
;     ...
;     wtrans(p.in[25] + (size_t)l * 1024 * 1024, 1024, 1024, WB + WB_O, 1024, 0, tile);
.Lwpa_m7:
	s_sub_u32 s25, s13, 5632
	s_lshr_b32 s32, s25, 4
	s_and_b32 s50, s25, 15
	s_mov_b64 s[14:15], s[66:67]
	s_mul_i32 s87, s32, 262144
	s_lshl_b32 s88, s50, 8
	s_add_u32 s87, s87, s88
	s_add_u32 s14, s14, s87
	s_addc_u32 s15, s15, 0
	s_mov_b32 s52, 4096
	s_mov_b32 s53, 32768
	s_mov_b32 s80, 2048
	s_lshl_b32 s86, s50, 6
	s_mul_i32 s87, s86, 2048
	s_lshl_b32 s88, s32, 7
	s_add_u32 s87, s87, s88
	s_add_u32 s87, s87, 0x2c00000
	s_add_u32 s36, s70, s87
	s_addc_u32 s37, s71, 0
	s_branch .Lwpa_body0
.Lwpa_body0:
	v_mad_u32_u24 v7, v10, s52, v11
	v_add_u32_e32 v8, s52, v7
	v_mad_u32_u24 v9, v13, s80, v14
	s_mov_b64 s[44:45], s[14:15]
	global_load_dwordx4 v[16:19], v7, s[44:45]
	global_load_dwordx4 v[20:23], v8, s[44:45]
	s_add_u32 s44, s44, s53
	s_addc_u32 s45, s45, 0
	global_load_dwordx4 v[46:49], v7, s[44:45]
	global_load_dwordx4 v[50:53], v8, s[44:45]
	s_add_u32 s44, s44, s53
	s_addc_u32 s45, s45, 0
	global_load_dwordx4 v[54:57], v7, s[44:45]
	global_load_dwordx4 v[58:61], v8, s[44:45]
	s_add_u32 s44, s44, s53
	s_addc_u32 s45, s45, 0
	global_load_dwordx4 v[62:65], v7, s[44:45]
	global_load_dwordx4 v[66:69], v8, s[44:45]
	s_add_u32 s44, s44, s53
	s_addc_u32 s45, s45, 0
	global_load_dwordx4 v[70:73], v7, s[44:45]
	global_load_dwordx4 v[74:77], v8, s[44:45]
	s_add_u32 s44, s44, s53
	s_addc_u32 s45, s45, 0
	global_load_dwordx4 v[88:91], v7, s[44:45]
	global_load_dwordx4 v[92:95], v8, s[44:45]
	s_add_u32 s44, s44, s53
	s_addc_u32 s45, s45, 0
	global_load_dwordx4 v[96:99], v7, s[44:45]
	global_load_dwordx4 v[100:103], v8, s[44:45]
	s_add_u32 s44, s44, s53
	s_addc_u32 s45, s45, 0
	global_load_dwordx4 v[106:109], v7, s[44:45]
	global_load_dwordx4 v[110:113], v8, s[44:45]
	s_waitcnt vmcnt(14)
	v_cvt_pk_bf16_f32 v24, v16, v20
	ds_write_b32 v2, v24 offset:0
	v_cvt_pk_bf16_f32 v78, v17, v21
	ds_write_b32 v2, v78 offset:132
	v_cvt_pk_bf16_f32 v104, v18, v22
	ds_write_b32 v2, v104 offset:264
	v_cvt_pk_bf16_f32 v114, v19, v23
	ds_write_b32 v2, v114 offset:396
	s_waitcnt vmcnt(12)
	v_cvt_pk_bf16_f32 v115, v46, v50
	ds_write_b32 v2, v115 offset:16
	v_cvt_pk_bf16_f32 v116, v47, v51
	ds_write_b32 v2, v116 offset:148
	v_cvt_pk_bf16_f32 v117, v48, v52
	ds_write_b32 v2, v117 offset:280
	v_cvt_pk_bf16_f32 v118, v49, v53
	ds_write_b32 v2, v118 offset:412
	s_waitcnt vmcnt(10)
	v_cvt_pk_bf16_f32 v24, v54, v58
	ds_write_b32 v2, v24 offset:32
	v_cvt_pk_bf16_f32 v78, v55, v59
	ds_write_b32 v2, v78 offset:164
	v_cvt_pk_bf16_f32 v104, v56, v60
	ds_write_b32 v2, v104 offset:296
	v_cvt_pk_bf16_f32 v114, v57, v61
	ds_write_b32 v2, v114 offset:428
	s_waitcnt vmcnt(8)
	v_cvt_pk_bf16_f32 v115, v62, v66
	ds_write_b32 v2, v115 offset:48
	v_cvt_pk_bf16_f32 v116, v63, v67
	ds_write_b32 v2, v116 offset:180
	v_cvt_pk_bf16_f32 v117, v64, v68
	ds_write_b32 v2, v117 offset:312
	v_cvt_pk_bf16_f32 v118, v65, v69
	ds_write_b32 v2, v118 offset:444
	s_waitcnt vmcnt(6)
	v_cvt_pk_bf16_f32 v24, v70, v74
	ds_write_b32 v2, v24 offset:64
	v_cvt_pk_bf16_f32 v78, v71, v75
	ds_write_b32 v2, v78 offset:196
	v_cvt_pk_bf16_f32 v104, v72, v76
	ds_write_b32 v2, v104 offset:328
	v_cvt_pk_bf16_f32 v114, v73, v77
	ds_write_b32 v2, v114 offset:460
	s_waitcnt vmcnt(4)
	v_cvt_pk_bf16_f32 v115, v88, v92
	ds_write_b32 v2, v115 offset:80
	v_cvt_pk_bf16_f32 v116, v89, v93
	ds_write_b32 v2, v116 offset:212
	v_cvt_pk_bf16_f32 v117, v90, v94
	ds_write_b32 v2, v117 offset:344
	v_cvt_pk_bf16_f32 v118, v91, v95
	ds_write_b32 v2, v118 offset:476
	s_waitcnt vmcnt(2)
	v_cvt_pk_bf16_f32 v24, v96, v100
	ds_write_b32 v2, v24 offset:96
	v_cvt_pk_bf16_f32 v78, v97, v101
	ds_write_b32 v2, v78 offset:228
	v_cvt_pk_bf16_f32 v104, v98, v102
	ds_write_b32 v2, v104 offset:360
	v_cvt_pk_bf16_f32 v114, v99, v103
	ds_write_b32 v2, v114 offset:492
	s_waitcnt vmcnt(0)
	v_cvt_pk_bf16_f32 v115, v106, v110
	ds_write_b32 v2, v115 offset:112
	v_cvt_pk_bf16_f32 v116, v107, v111
	ds_write_b32 v2, v116 offset:244
	v_cvt_pk_bf16_f32 v117, v108, v112
	ds_write_b32 v2, v117 offset:376
	v_cvt_pk_bf16_f32 v118, v109, v113
	ds_write_b32 v2, v118 offset:508
	ds_read_b32 v120, v4 offset:0
	ds_read_b32 v121, v4 offset:264
	ds_read_b32 v122, v4 offset:528
	ds_read_b32 v123, v4 offset:792
	ds_read_b32 v124, v4 offset:1056
	ds_read_b32 v125, v4 offset:1320
	ds_read_b32 v126, v4 offset:1584
	ds_read_b32 v127, v4 offset:1848
	ds_read_b32 v128, v4 offset:2112
	ds_read_b32 v129, v4 offset:2376
	ds_read_b32 v130, v4 offset:2640
	ds_read_b32 v131, v4 offset:2904
	ds_read_b32 v132, v4 offset:3168
	ds_read_b32 v133, v4 offset:3432
	ds_read_b32 v134, v4 offset:3696
	ds_read_b32 v135, v4 offset:3960
	ds_read_b32 v136, v4 offset:4224
	ds_read_b32 v137, v4 offset:4488
	ds_read_b32 v138, v4 offset:4752
	ds_read_b32 v139, v4 offset:5016
	ds_read_b32 v140, v4 offset:5280
	ds_read_b32 v141, v4 offset:5544
	ds_read_b32 v142, v4 offset:5808
	ds_read_b32 v143, v4 offset:6072
	ds_read_b32 v144, v4 offset:6336
	ds_read_b32 v145, v4 offset:6600
	ds_read_b32 v146, v4 offset:6864
	ds_read_b32 v147, v4 offset:7128
	ds_read_b32 v148, v4 offset:7392
	ds_read_b32 v149, v4 offset:7656
	ds_read_b32 v150, v4 offset:7920
	ds_read_b32 v151, v4 offset:8184
	s_mov_b64 s[48:49], s[36:37]
	s_waitcnt lgkmcnt(15)
	global_store_dword v9, v120, s[48:49]
	s_mul_i32 s87, s80, 2
	s_add_u32 s48, s48, s87
	s_addc_u32 s49, s49, 0
	global_store_dword v9, v121, s[48:49]
	s_mul_i32 s87, s80, 2
	s_add_u32 s48, s48, s87
	s_addc_u32 s49, s49, 0
	global_store_dword v9, v122, s[48:49]
	s_mul_i32 s87, s80, 2
	s_add_u32 s48, s48, s87
	s_addc_u32 s49, s49, 0
	global_store_dword v9, v123, s[48:49]
	s_mul_i32 s87, s80, 2
	s_add_u32 s48, s48, s87
	s_addc_u32 s49, s49, 0
	global_store_dword v9, v124, s[48:49]
	s_mul_i32 s87, s80, 2
	s_add_u32 s48, s48, s87
	s_addc_u32 s49, s49, 0
	global_store_dword v9, v125, s[48:49]
	s_mul_i32 s87, s80, 2
	s_add_u32 s48, s48, s87
	s_addc_u32 s49, s49, 0
	global_store_dword v9, v126, s[48:49]
	s_mul_i32 s87, s80, 2
	s_add_u32 s48, s48, s87
	s_addc_u32 s49, s49, 0
	global_store_dword v9, v127, s[48:49]
	s_waitcnt lgkmcnt(15)
; __device__ __forceinline__ unsigned pk_bf16(float lo, float hi) { const f32x2_t f = {lo, hi}; return __builtin_bit_cast(unsigned, __builtin_convertvector(f, bf16x2_t)); }
; __device__ __forceinline__ int obid() { int b = blockIdx.x; asm volatile("" : "+s"(b)); return b; }
; __device__ __forceinline__ void wtrans(const float* __restrict__ src, int K, int N, bf16_t* __restrict__ dst, int ldd, int mode, LAS float* tile) {
;     ...
;     for (int t = obid(); t < nt; t += gridDim.x) {
;         const int k0 = (t / tn) << 6, c0 = (t % tn) << 6;
;         {
; #pragma unroll
;           for (int i = 0; i < 2; ++i) { const int e = tid + 512 * i, kl = e >> 4, c4 = (e & 15) * 4;
;               const f32x4 v4 = *(const f32x4*)(src + (size_t)(k0 + kl) * N + c0 + c4);
;               tile[kl * 65 + c4] = v4[0]; tile[kl * 65 + c4 + 1] = v4[1]; tile[kl * 65 + c4 + 2] = v4[2]; tile[kl * 65 + c4 + 3] = v4[3]; } }
;         __syncthreads();
;         { const int kp = tid & 31, cl0 = tid >> 5;
; #pragma unroll
;           for (int i = 0; i < 4; ++i) { const int cl = cl0 + 16 * i, c = c0 + cl; const int R = mode ? gu_row(c) : c;
;               *(unsigned*)(dst + (size_t)R * ldd + k0 + 2 * kp) = pk_bf16(tile[(2 * kp) * 65 + cl], tile[(2 * kp + 1) * 65 + cl]); } }
	s_mul_i32 s87, s80, 2
	s_add_u32 s48, s48, s87
	s_addc_u32 s49, s49, 0
	global_store_dword v9, v128, s[48:49]
	s_mul_i32 s87, s80, 2
	s_add_u32 s48, s48, s87
	s_addc_u32 s49, s49, 0
	global_store_dword v9, v129, s[48:49]
	s_mul_i32 s87, s80, 2
	s_add_u32 s48, s48, s87
	s_addc_u32 s49, s49, 0
	global_store_dword v9, v130, s[48:49]
	s_mul_i32 s87, s80, 2
	s_add_u32 s48, s48, s87
	s_addc_u32 s49, s49, 0
	global_store_dword v9, v131, s[48:49]
	s_mul_i32 s87, s80, 2
	s_add_u32 s48, s48, s87
	s_addc_u32 s49, s49, 0
	global_store_dword v9, v132, s[48:49]
	s_mul_i32 s87, s80, 2
	s_add_u32 s48, s48, s87
	s_addc_u32 s49, s49, 0
	global_store_dword v9, v133, s[48:49]
	s_mul_i32 s87, s80, 2
	s_add_u32 s48, s48, s87
	s_addc_u32 s49, s49, 0
	global_store_dword v9, v134, s[48:49]
	s_mul_i32 s87, s80, 2
	s_add_u32 s48, s48, s87
	s_addc_u32 s49, s49, 0
	global_store_dword v9, v135, s[48:49]
	s_waitcnt lgkmcnt(8)
	s_mul_i32 s87, s80, 2
	s_add_u32 s48, s48, s87
	s_addc_u32 s49, s49, 0
	global_store_dword v9, v136, s[48:49]
	s_mul_i32 s87, s80, 2
	s_add_u32 s48, s48, s87
	s_addc_u32 s49, s49, 0
	global_store_dword v9, v137, s[48:49]
	s_mul_i32 s87, s80, 2
	s_add_u32 s48, s48, s87
	s_addc_u32 s49, s49, 0
	global_store_dword v9, v138, s[48:49]
	s_mul_i32 s87, s80, 2
	s_add_u32 s48, s48, s87
	s_addc_u32 s49, s49, 0
	global_store_dword v9, v139, s[48:49]
	s_mul_i32 s87, s80, 2
	s_add_u32 s48, s48, s87
	s_addc_u32 s49, s49, 0
	global_store_dword v9, v140, s[48:49]
	s_mul_i32 s87, s80, 2
	s_add_u32 s48, s48, s87
	s_addc_u32 s49, s49, 0
	global_store_dword v9, v141, s[48:49]
	s_mul_i32 s87, s80, 2
	s_add_u32 s48, s48, s87
	s_addc_u32 s49, s49, 0
	global_store_dword v9, v142, s[48:49]
	s_mul_i32 s87, s80, 2
	s_add_u32 s48, s48, s87
	s_addc_u32 s49, s49, 0
	global_store_dword v9, v143, s[48:49]
	s_waitcnt lgkmcnt(0)
	s_mul_i32 s87, s80, 2
	s_add_u32 s48, s48, s87
	s_addc_u32 s49, s49, 0
	global_store_dword v9, v144, s[48:49]
	s_mul_i32 s87, s80, 2
	s_add_u32 s48, s48, s87
	s_addc_u32 s49, s49, 0
	global_store_dword v9, v145, s[48:49]
	s_mul_i32 s87, s80, 2
	s_add_u32 s48, s48, s87
	s_addc_u32 s49, s49, 0
	global_store_dword v9, v146, s[48:49]
	s_mul_i32 s87, s80, 2
	s_add_u32 s48, s48, s87
	s_addc_u32 s49, s49, 0
	global_store_dword v9, v147, s[48:49]
	s_mul_i32 s87, s80, 2
	s_add_u32 s48, s48, s87
	s_addc_u32 s49, s49, 0
	global_store_dword v9, v148, s[48:49]
	s_mul_i32 s87, s80, 2
	s_add_u32 s48, s48, s87
	s_addc_u32 s49, s49, 0
	global_store_dword v9, v149, s[48:49]
	s_mul_i32 s87, s80, 2
	s_add_u32 s48, s48, s87
	s_addc_u32 s49, s49, 0
	global_store_dword v9, v150, s[48:49]
	s_mul_i32 s87, s80, 2
	s_add_u32 s48, s48, s87
	s_addc_u32 s49, s49, 0
	global_store_dword v9, v151, s[48:49]
	s_add_u32 s13, s13, 2048
	s_branch .Lwpa_tile
.Lwpa_body1:
	v_mad_u32_u24 v7, v10, s52, v11
	v_add_u32_e32 v8, s52, v7
	v_mad_u32_u24 v9, v13, s80, v14
	s_mov_b64 s[44:45], s[14:15]
	global_load_dwordx4 v[16:19], v7, s[44:45]
	global_load_dwordx4 v[20:23], v8, s[44:45]
	s_add_u32 s44, s44, s53
	s_addc_u32 s45, s45, 0
	global_load_dwordx4 v[46:49], v7, s[44:45]
	global_load_dwordx4 v[50:53], v8, s[44:45]
	s_add_u32 s44, s44, s53
	s_addc_u32 s45, s45, 0
	global_load_dwordx4 v[54:57], v7, s[44:45]
	global_load_dwordx4 v[58:61], v8, s[44:45]
	s_add_u32 s44, s44, s53
	s_addc_u32 s45, s45, 0
	global_load_dwordx4 v[62:65], v7, s[44:45]
	global_load_dwordx4 v[66:69], v8, s[44:45]
	s_add_u32 s44, s44, s53
	s_addc_u32 s45, s45, 0
	global_load_dwordx4 v[70:73], v7, s[44:45]
	global_load_dwordx4 v[74:77], v8, s[44:45]
	s_add_u32 s44, s44, s53
	s_addc_u32 s45, s45, 0
	global_load_dwordx4 v[88:91], v7, s[44:45]
	global_load_dwordx4 v[92:95], v8, s[44:45]
	s_add_u32 s44, s44, s53
	s_addc_u32 s45, s45, 0
	global_load_dwordx4 v[96:99], v7, s[44:45]
	global_load_dwordx4 v[100:103], v8, s[44:45]
	s_add_u32 s44, s44, s53
	s_addc_u32 s45, s45, 0
	global_load_dwordx4 v[106:109], v7, s[44:45]
	global_load_dwordx4 v[110:113], v8, s[44:45]
	s_waitcnt vmcnt(14)
	v_cvt_pk_bf16_f32 v24, v16, v20
	ds_write_b32 v2, v24 offset:0
	v_cvt_pk_bf16_f32 v78, v17, v21
	ds_write_b32 v2, v78 offset:132
	v_cvt_pk_bf16_f32 v104, v18, v22
	ds_write_b32 v2, v104 offset:264
	v_cvt_pk_bf16_f32 v114, v19, v23
	ds_write_b32 v2, v114 offset:396
	s_waitcnt vmcnt(12)
	v_cvt_pk_bf16_f32 v115, v46, v50
	ds_write_b32 v2, v115 offset:16
	v_cvt_pk_bf16_f32 v116, v47, v51
	ds_write_b32 v2, v116 offset:148
	v_cvt_pk_bf16_f32 v117, v48, v52
	ds_write_b32 v2, v117 offset:280
	v_cvt_pk_bf16_f32 v118, v49, v53
	ds_write_b32 v2, v118 offset:412
	s_waitcnt vmcnt(10)
	v_cvt_pk_bf16_f32 v24, v54, v58
	ds_write_b32 v2, v24 offset:32
	v_cvt_pk_bf16_f32 v78, v55, v59
	ds_write_b32 v2, v78 offset:164
	v_cvt_pk_bf16_f32 v104, v56, v60
	ds_write_b32 v2, v104 offset:296
	v_cvt_pk_bf16_f32 v114, v57, v61
	ds_write_b32 v2, v114 offset:428
	s_waitcnt vmcnt(8)
	v_cvt_pk_bf16_f32 v115, v62, v66
	ds_write_b32 v2, v115 offset:48
	v_cvt_pk_bf16_f32 v116, v63, v67
	ds_write_b32 v2, v116 offset:180
	v_cvt_pk_bf16_f32 v117, v64, v68
	ds_write_b32 v2, v117 offset:312
	v_cvt_pk_bf16_f32 v118, v65, v69
	ds_write_b32 v2, v118 offset:444
	s_waitcnt vmcnt(6)
	v_cvt_pk_bf16_f32 v24, v70, v74
	ds_write_b32 v2, v24 offset:64
	v_cvt_pk_bf16_f32 v78, v71, v75
	ds_write_b32 v2, v78 offset:196
	v_cvt_pk_bf16_f32 v104, v72, v76
	ds_write_b32 v2, v104 offset:328
	v_cvt_pk_bf16_f32 v114, v73, v77
	ds_write_b32 v2, v114 offset:460
	s_waitcnt vmcnt(4)
; #define LAS __attribute__((address_space(3)))
; __device__ __forceinline__ unsigned pk_bf16(float lo, float hi) { const f32x2_t f = {lo, hi}; return __builtin_bit_cast(unsigned, __builtin_convertvector(f, bf16x2_t)); }
; __device__ __forceinline__ int otid() { int t = threadIdx.x; asm volatile("" : "+v"(t)); return t; }
; __device__ __forceinline__ int obid() { int b = blockIdx.x; asm volatile("" : "+s"(b)); return b; }
; __device__ __forceinline__ void wtrans(const float* __restrict__ src, int K, int N, bf16_t* __restrict__ dst, int ldd, int mode, LAS float* tile) {
;     const int tid = otid(), tn = N >> 6, nt = (K >> 6) * tn;
;     for (int t = obid(); t < nt; t += gridDim.x) {
;         const int k0 = (t / tn) << 6, c0 = (t % tn) << 6;
;         {
; #pragma unroll
;           for (int i = 0; i < 2; ++i) { const int e = tid + 512 * i, kl = e >> 4, c4 = (e & 15) * 4;
;               const f32x4 v4 = *(const f32x4*)(src + (size_t)(k0 + kl) * N + c0 + c4);
;               tile[kl * 65 + c4] = v4[0]; tile[kl * 65 + c4 + 1] = v4[1]; tile[kl * 65 + c4 + 2] = v4[2]; tile[kl * 65 + c4 + 3] = v4[3]; } }
;         __syncthreads();
;         { const int kp = tid & 31, cl0 = tid >> 5;
; #pragma unroll
;           for (int i = 0; i < 4; ++i) { const int cl = cl0 + 16 * i, c = c0 + cl; const int R = mode ? gu_row(c) : c;
;               *(unsigned*)(dst + (size_t)R * ldd + k0 + 2 * kp) = pk_bf16(tile[(2 * kp) * 65 + cl], tile[(2 * kp + 1) * 65 + cl]); } }
	v_cvt_pk_bf16_f32 v115, v88, v92
	ds_write_b32 v2, v115 offset:80
	v_cvt_pk_bf16_f32 v116, v89, v93
	ds_write_b32 v2, v116 offset:212
	v_cvt_pk_bf16_f32 v117, v90, v94
	ds_write_b32 v2, v117 offset:344
	v_cvt_pk_bf16_f32 v118, v91, v95
	ds_write_b32 v2, v118 offset:476
	s_waitcnt vmcnt(2)
	v_cvt_pk_bf16_f32 v24, v96, v100
	ds_write_b32 v2, v24 offset:96
	v_cvt_pk_bf16_f32 v78, v97, v101
	ds_write_b32 v2, v78 offset:228
	v_cvt_pk_bf16_f32 v104, v98, v102
	ds_write_b32 v2, v104 offset:360
	v_cvt_pk_bf16_f32 v114, v99, v103
	ds_write_b32 v2, v114 offset:492
	s_waitcnt vmcnt(0)
	v_cvt_pk_bf16_f32 v115, v106, v110
	ds_write_b32 v2, v115 offset:112
	v_cvt_pk_bf16_f32 v116, v107, v111
	ds_write_b32 v2, v116 offset:244
	v_cvt_pk_bf16_f32 v117, v108, v112
	ds_write_b32 v2, v117 offset:376
	v_cvt_pk_bf16_f32 v118, v109, v113
	ds_write_b32 v2, v118 offset:508
	ds_read_b32 v120, v4 offset:0
	ds_read_b32 v121, v4 offset:264
	ds_read_b32 v122, v4 offset:528
	ds_read_b32 v123, v4 offset:792
	ds_read_b32 v124, v4 offset:1056
	ds_read_b32 v125, v4 offset:1320
	ds_read_b32 v126, v4 offset:1584
	ds_read_b32 v127, v4 offset:1848
	ds_read_b32 v128, v4 offset:2112
	ds_read_b32 v129, v4 offset:2376
	ds_read_b32 v130, v4 offset:2640
	ds_read_b32 v131, v4 offset:2904
	ds_read_b32 v132, v4 offset:3168
	ds_read_b32 v133, v4 offset:3432
	ds_read_b32 v134, v4 offset:3696
	ds_read_b32 v135, v4 offset:3960
	ds_read_b32 v136, v4 offset:4224
	ds_read_b32 v137, v4 offset:4488
	ds_read_b32 v138, v4 offset:4752
	ds_read_b32 v139, v4 offset:5016
	ds_read_b32 v140, v4 offset:5280
	ds_read_b32 v141, v4 offset:5544
	ds_read_b32 v142, v4 offset:5808
	ds_read_b32 v143, v4 offset:6072
	ds_read_b32 v144, v4 offset:6336
	ds_read_b32 v145, v4 offset:6600
	ds_read_b32 v146, v4 offset:6864
	ds_read_b32 v147, v4 offset:7128
	ds_read_b32 v148, v4 offset:7392
	ds_read_b32 v149, v4 offset:7656
	ds_read_b32 v150, v4 offset:7920
	ds_read_b32 v151, v4 offset:8184
	s_mov_b64 s[48:49], s[36:37]
	s_waitcnt lgkmcnt(15)
	global_store_dword v9, v120, s[48:49]
	s_mul_i32 s87, s80, 2
	s_add_u32 s48, s48, s87
	s_addc_u32 s49, s49, 0
	global_store_dword v9, v121, s[48:49]
	s_mul_i32 s87, s80, 126
	s_add_u32 s48, s48, s87
	s_addc_u32 s49, s49, 0
	global_store_dword v9, v122, s[48:49]
	s_mul_i32 s87, s80, 2
	s_add_u32 s48, s48, s87
	s_addc_u32 s49, s49, 0
	global_store_dword v9, v123, s[48:49]
	s_mul_i32 s87, s80, 126
	s_sub_u32 s48, s48, s87
	s_subb_u32 s49, s49, 0
	global_store_dword v9, v124, s[48:49]
	s_mul_i32 s87, s80, 2
	s_add_u32 s48, s48, s87
	s_addc_u32 s49, s49, 0
	global_store_dword v9, v125, s[48:49]
	s_mul_i32 s87, s80, 126
	s_add_u32 s48, s48, s87
	s_addc_u32 s49, s49, 0
	global_store_dword v9, v126, s[48:49]
	s_mul_i32 s87, s80, 2
	s_add_u32 s48, s48, s87
	s_addc_u32 s49, s49, 0
	global_store_dword v9, v127, s[48:49]
	s_waitcnt lgkmcnt(15)
	s_mul_i32 s87, s80, 126
	s_sub_u32 s48, s48, s87
	s_subb_u32 s49, s49, 0
	global_store_dword v9, v128, s[48:49]
	s_mul_i32 s87, s80, 2
	s_add_u32 s48, s48, s87
	s_addc_u32 s49, s49, 0
	global_store_dword v9, v129, s[48:49]
	s_mul_i32 s87, s80, 126
	s_add_u32 s48, s48, s87
	s_addc_u32 s49, s49, 0
	global_store_dword v9, v130, s[48:49]
	s_mul_i32 s87, s80, 2
	s_add_u32 s48, s48, s87
	s_addc_u32 s49, s49, 0
	global_store_dword v9, v131, s[48:49]
	s_mul_i32 s87, s80, 126
	s_sub_u32 s48, s48, s87
	s_subb_u32 s49, s49, 0
	global_store_dword v9, v132, s[48:49]
	s_mul_i32 s87, s80, 2
	s_add_u32 s48, s48, s87
	s_addc_u32 s49, s49, 0
	global_store_dword v9, v133, s[48:49]
	s_mul_i32 s87, s80, 126
	s_add_u32 s48, s48, s87
	s_addc_u32 s49, s49, 0
	global_store_dword v9, v134, s[48:49]
	s_mul_i32 s87, s80, 2
	s_add_u32 s48, s48, s87
	s_addc_u32 s49, s49, 0
	global_store_dword v9, v135, s[48:49]
	s_waitcnt lgkmcnt(8)
	s_mul_i32 s87, s80, 110
	s_sub_u32 s48, s48, s87
	s_subb_u32 s49, s49, 0
	global_store_dword v9, v136, s[48:49]
	s_mul_i32 s87, s80, 2
	s_add_u32 s48, s48, s87
	s_addc_u32 s49, s49, 0
	global_store_dword v9, v137, s[48:49]
	s_mul_i32 s87, s80, 126
	s_add_u32 s48, s48, s87
	s_addc_u32 s49, s49, 0
	global_store_dword v9, v138, s[48:49]
	s_mul_i32 s87, s80, 2
	s_add_u32 s48, s48, s87
	s_addc_u32 s49, s49, 0
	global_store_dword v9, v139, s[48:49]
	s_mul_i32 s87, s80, 126
	s_sub_u32 s48, s48, s87
	s_subb_u32 s49, s49, 0
	global_store_dword v9, v140, s[48:49]
	s_mul_i32 s87, s80, 2
	s_add_u32 s48, s48, s87
	s_addc_u32 s49, s49, 0
	global_store_dword v9, v141, s[48:49]
	s_mul_i32 s87, s80, 126
	s_add_u32 s48, s48, s87
	s_addc_u32 s49, s49, 0
	global_store_dword v9, v142, s[48:49]
	s_mul_i32 s87, s80, 2
	s_add_u32 s48, s48, s87
	s_addc_u32 s49, s49, 0
	global_store_dword v9, v143, s[48:49]
	s_waitcnt lgkmcnt(0)
	s_mul_i32 s87, s80, 126
	s_sub_u32 s48, s48, s87
	s_subb_u32 s49, s49, 0
	global_store_dword v9, v144, s[48:49]
	s_mul_i32 s87, s80, 2
	s_add_u32 s48, s48, s87
	s_addc_u32 s49, s49, 0
	global_store_dword v9, v145, s[48:49]
	s_mul_i32 s87, s80, 126
	s_add_u32 s48, s48, s87
	s_addc_u32 s49, s49, 0
	global_store_dword v9, v146, s[48:49]
	s_mul_i32 s87, s80, 2
	s_add_u32 s48, s48, s87
	s_addc_u32 s49, s49, 0
	global_store_dword v9, v147, s[48:49]
	s_mul_i32 s87, s80, 126
	s_sub_u32 s48, s48, s87
	s_subb_u32 s49, s49, 0
	global_store_dword v9, v148, s[48:49]
	s_mul_i32 s87, s80, 2
	s_add_u32 s48, s48, s87
	s_addc_u32 s49, s49, 0
	global_store_dword v9, v149, s[48:49]
	s_mul_i32 s87, s80, 126
	s_add_u32 s48, s48, s87
	s_addc_u32 s49, s49, 0
	global_store_dword v9, v150, s[48:49]
	s_mul_i32 s87, s80, 2
	s_add_u32 s48, s48, s87
	s_addc_u32 s49, s49, 0
	global_store_dword v9, v151, s[48:49]
	s_add_u32 s13, s13, 2048
	s_branch .Lwpa_tile
.Lwpa_done:
	s_waitcnt vmcnt(0) lgkmcnt(0)

; __device__ __forceinline__ void unpack8(const u32x4 w, f32x4& a, f32x4& b) { a[0] = bf_lo(w.x); a[1] = bf_hi(w.x); a[2] = bf_lo(w.y); a[3] = bf_hi(w.y); b[0] = bf_lo(w.z); b[1] = bf_hi(w.z); b[2] = bf_lo(w.w); b[3] = bf_hi(w.w); }
; __device__ __forceinline__ void phase_ln(const float* RES, const bf16_t* DEL, float* X, bf16_t* XB, const float* g, const float* b, bool write_xb) {
;     ...
;     for (int base = w0; base < M_TOK; base += nw * 4) {
;         f32x4 v[4][4];
; #pragma unroll
;         for (int r = 0; r < 4; ++r) { const float* xr = RES + (size_t)(base + r * nw) * 1024; const bf16_t* dr = DEL + (size_t)(base + r * nw) * 1024;
; #pragma unroll
;             for (int i = 0; i < 2; ++i) { const int c = i * 512 + lane * 8; const f32x4 xa = *(const f32x4*)(xr + c), xb2 = *(const f32x4*)(xr + c + 4); const u32x4 d4 = *(const u32x4*)(dr + c);
;                 f32x4 da, db; unpack8(d4, da, db); v[r][2 * i] = xa * ALPHA + da; v[r][2 * i + 1] = xb2 * ALPHA + db; } }
.LBB0_220:
	v_ashrrev_i32_e32 v1, 31, v0
	v_lshlrev_b64 v[2:3], 12, v[0:1]
	v_lshlrev_b64 v[4:5], 11, v[0:1]
	v_lshl_add_u64 v[2:3], v[34:35], 0, v[2:3]
	v_lshl_add_u64 v[4:5], v[36:37], 0, v[4:5]
	global_load_dwordx4 v[138:141], v[2:3], off offset:16
	global_load_dwordx4 v[142:145], v[2:3], off
	global_load_dwordx4 v[146:149], v[4:5], off
	global_load_dwordx4 v[150:153], v[2:3], off offset:2064
	global_load_dwordx4 v[154:157], v[2:3], off offset:2048
	global_load_dwordx4 v[158:161], v[4:5], off offset:1024
	v_add_u32_e32 v6, s16, v0
	v_ashrrev_i32_e32 v7, 31, v6
	v_lshlrev_b64 v[2:3], 12, v[6:7]
	v_lshlrev_b64 v[4:5], 11, v[6:7]
	v_lshl_add_u64 v[2:3], v[34:35], 0, v[2:3]
	v_lshl_add_u64 v[4:5], v[36:37], 0, v[4:5]
	global_load_dwordx4 v[162:165], v[2:3], off offset:16
	global_load_dwordx4 v[166:169], v[2:3], off
	global_load_dwordx4 v[170:173], v[4:5], off
	global_load_dwordx4 v[174:177], v[2:3], off offset:2064
	global_load_dwordx4 v[186:189], v[2:3], off offset:2048
	global_load_dwordx4 v[194:197], v[4:5], off offset:1024
	v_add_u32_e32 v6, s25, v0
	v_ashrrev_i32_e32 v7, 31, v6
	v_lshlrev_b64 v[2:3], 12, v[6:7]
	v_lshlrev_b64 v[4:5], 11, v[6:7]
	v_lshl_add_u64 v[2:3], v[34:35], 0, v[2:3]
	v_lshl_add_u64 v[4:5], v[36:37], 0, v[4:5]
	global_load_dwordx4 v[198:201], v[2:3], off offset:16
	global_load_dwordx4 v[202:205], v[2:3], off
	global_load_dwordx4 v[206:209], v[4:5], off
	global_load_dwordx4 v[210:213], v[2:3], off offset:2064
	global_load_dwordx4 v[220:223], v[2:3], off offset:2048
	global_load_dwordx4 v[224:227], v[4:5], off offset:1024
	v_add_u32_e32 v6, s48, v0
	v_ashrrev_i32_e32 v7, 31, v6
	v_lshlrev_b64 v[2:3], 12, v[6:7]
	v_lshlrev_b64 v[4:5], 11, v[6:7]
	v_lshl_add_u64 v[2:3], v[34:35], 0, v[2:3]
	v_lshl_add_u64 v[4:5], v[36:37], 0, v[4:5]
	global_load_dwordx4 v[228:231], v[2:3], off offset:16
	global_load_dwordx4 v[232:235], v[2:3], off
	global_load_dwordx4 v[236:239], v[4:5], off
	global_load_dwordx4 v[244:247], v[2:3], off offset:2064
	global_load_dwordx4 v[248:251], v[2:3], off offset:2048
	v_mov_b32_e32 v8, v4
	v_mov_b32_e32 v9, v5
	v_add_u32_e32 v80, s25, v0
	v_ashrrev_i32_e32 v81, 31, v80
	v_add_u32_e32 v84, s48, v0
	v_ashrrev_i32_e32 v85, 31, v84
	v_lshlrev_b64 v[38:39], 10, v[0:1]
	v_or_b32_e32 v134, v38, v26
	v_mov_b32_e32 v135, v39
	v_cndmask_b32_e64 v13, 0, 1, s[42:43]
	v_cmp_ne_u32_e64 s[38:39], 1, v13
	s_waitcnt vmcnt(20)
	v_lshlrev_b32_e32 v20, 16, v146
	v_and_b32_e32 v21, 0xffff0000, v146
	v_lshlrev_b32_e32 v14, 16, v147
	v_and_b32_e32 v15, 0xffff0000, v147
	v_lshlrev_b32_e32 v24, 16, v148
	v_and_b32_e32 v25, 0xffff0000, v148
	v_lshlrev_b32_e32 v16, 16, v149
	v_and_b32_e32 v17, 0xffff0000, v149
	v_pk_fma_f32 v[18:19], v[144:145], s[4:5], v[14:15] op_sel_hi:[1,0,1]
	v_pk_fma_f32 v[20:21], v[142:143], s[4:5], v[20:21] op_sel_hi:[1,0,1]
	v_pk_fma_f32 v[22:23], v[140:141], s[4:5], v[16:17] op_sel_hi:[1,0,1]
	v_pk_fma_f32 v[24:25], v[138:139], s[4:5], v[24:25] op_sel_hi:[1,0,1]
	global_load_dwordx4 v[146:149], v[8:9], off offset:1024
	s_waitcnt vmcnt(18)
	v_lshlrev_b32_e32 v40, 16, v160
	v_and_b32_e32 v41, 0xffff0000, v160
	v_pk_fma_f32 v[46:47], v[150:151], s[4:5], v[40:41] op_sel_hi:[1,0,1]
	v_add_u32_e32 v40, s16, v0
	v_lshlrev_b32_e32 v10, 16, v158
	v_and_b32_e32 v11, 0xffff0000, v158
	v_lshlrev_b32_e32 v14, 16, v159
	v_and_b32_e32 v15, 0xffff0000, v159
	v_ashrrev_i32_e32 v41, 31, v40
	v_pk_fma_f32 v[44:45], v[156:157], s[4:5], v[14:15] op_sel_hi:[1,0,1]
	v_lshlrev_b32_e32 v16, 16, v161
	v_and_b32_e32 v17, 0xffff0000, v161
	v_pk_fma_f32 v[48:49], v[154:155], s[4:5], v[10:11] op_sel_hi:[1,0,1]
	v_pk_fma_f32 v[42:43], v[152:153], s[4:5], v[16:17] op_sel_hi:[1,0,1]
	s_waitcnt vmcnt(15)
	v_lshlrev_b32_e32 v52, 16, v170
	v_and_b32_e32 v53, 0xffff0000, v170
	v_lshlrev_b32_e32 v14, 16, v171
	v_and_b32_e32 v15, 0xffff0000, v171
	v_lshlrev_b32_e32 v54, 16, v172
	v_and_b32_e32 v55, 0xffff0000, v172
	v_lshlrev_b32_e32 v16, 16, v173
	v_and_b32_e32 v17, 0xffff0000, v173
	v_pk_fma_f32 v[70:71], v[168:169], s[4:5], v[14:15] op_sel_hi:[1,0,1]
	v_pk_fma_f32 v[72:73], v[166:167], s[4:5], v[52:53] op_sel_hi:[1,0,1]
	v_pk_fma_f32 v[66:67], v[164:165], s[4:5], v[16:17] op_sel_hi:[1,0,1]
	v_pk_fma_f32 v[68:69], v[162:163], s[4:5], v[54:55] op_sel_hi:[1,0,1]
	s_waitcnt vmcnt(12)
	v_lshlrev_b32_e32 v10, 16, v194
	v_and_b32_e32 v11, 0xffff0000, v194
	v_lshlrev_b32_e32 v14, 16, v195
	v_and_b32_e32 v15, 0xffff0000, v195
	v_lshlrev_b32_e32 v52, 16, v196
	v_and_b32_e32 v53, 0xffff0000, v196
	v_pk_fma_f32 v[54:55], v[188:189], s[4:5], v[14:15] op_sel_hi:[1,0,1]
	v_pk_fma_f32 v[52:53], v[174:175], s[4:5], v[52:53] op_sel_hi:[1,0,1]
	v_lshlrev_b32_e32 v16, 16, v197
	v_and_b32_e32 v17, 0xffff0000, v197
	v_pk_fma_f32 v[56:57], v[186:187], s[4:5], v[10:11] op_sel_hi:[1,0,1]
	v_pk_fma_f32 v[50:51], v[176:177], s[4:5], v[16:17] op_sel_hi:[1,0,1]
	s_waitcnt vmcnt(9)
	v_lshlrev_b32_e32 v60, 16, v206
	v_and_b32_e32 v61, 0xffff0000, v206
	v_lshlrev_b32_e32 v14, 16, v207
	v_and_b32_e32 v15, 0xffff0000, v207
	v_lshlrev_b32_e32 v62, 16, v208
	v_and_b32_e32 v63, 0xffff0000, v208
	v_lshlrev_b32_e32 v16, 16, v209
	v_and_b32_e32 v17, 0xffff0000, v209
	v_pk_fma_f32 v[78:79], v[204:205], s[4:5], v[14:15] op_sel_hi:[1,0,1]
	v_pk_fma_f32 v[82:83], v[202:203], s[4:5], v[60:61] op_sel_hi:[1,0,1]
	v_pk_fma_f32 v[74:75], v[200:201], s[4:5], v[16:17] op_sel_hi:[1,0,1]
	v_pk_fma_f32 v[76:77], v[198:199], s[4:5], v[62:63] op_sel_hi:[1,0,1]
	s_waitcnt vmcnt(6)
; __device__ __forceinline__ void unpack8(const u32x4 w, f32x4& a, f32x4& b) { a[0] = bf_lo(w.x); a[1] = bf_hi(w.x); a[2] = bf_lo(w.y); a[3] = bf_hi(w.y); b[0] = bf_lo(w.z); b[1] = bf_hi(w.z); b[2] = bf_lo(w.w); b[3] = bf_hi(w.w); }
; __device__ __forceinline__ void phase_ln(const float* RES, const bf16_t* DEL, float* X, bf16_t* XB, const float* g, const float* b, bool write_xb) {
;     ...
;         for (int r = 0; r < 4; ++r) { const float* xr = RES + (size_t)(base + r * nw) * 1024; const bf16_t* dr = DEL + (size_t)(base + r * nw) * 1024;
; #pragma unroll
;             for (int i = 0; i < 2; ++i) { const int c = i * 512 + lane * 8; const f32x4 xa = *(const f32x4*)(xr + c), xb2 = *(const f32x4*)(xr + c + 4); const u32x4 d4 = *(const u32x4*)(dr + c);
;                 f32x4 da, db; unpack8(d4, da, db); v[r][2 * i] = xa * ALPHA + da; v[r][2 * i + 1] = xb2 * ALPHA + db; } }
;         float mean[4], rs[4];
; #pragma unroll
;         for (int r = 0; r < 4; ++r) { float s = 0.f;
; #pragma unroll
;             for (int i = 0; i < 4; ++i) s += v[r][i][0] + v[r][i][1] + v[r][i][2] + v[r][i][3];
;             mean[r] = wave_sum(s) * (1.f / 1024.f); }
	v_lshlrev_b32_e32 v10, 16, v224
	v_and_b32_e32 v11, 0xffff0000, v224
	v_lshlrev_b32_e32 v14, 16, v225
	v_and_b32_e32 v15, 0xffff0000, v225
	v_lshlrev_b32_e32 v60, 16, v226
	v_and_b32_e32 v61, 0xffff0000, v226
	v_lshlrev_b32_e32 v16, 16, v227
	v_and_b32_e32 v17, 0xffff0000, v227
	v_pk_fma_f32 v[62:63], v[222:223], s[4:5], v[14:15] op_sel_hi:[1,0,1]
	v_pk_fma_f32 v[58:59], v[212:213], s[4:5], v[16:17] op_sel_hi:[1,0,1]
	v_pk_fma_f32 v[64:65], v[220:221], s[4:5], v[10:11] op_sel_hi:[1,0,1]
	v_pk_fma_f32 v[60:61], v[210:211], s[4:5], v[60:61] op_sel_hi:[1,0,1]
	s_waitcnt vmcnt(3)
	v_lshlrev_b32_e32 v86, 16, v236
	v_and_b32_e32 v87, 0xffff0000, v236
	v_lshlrev_b32_e32 v8, 16, v237
	v_and_b32_e32 v9, 0xffff0000, v237
	v_lshlrev_b32_e32 v88, 16, v238
	v_and_b32_e32 v89, 0xffff0000, v238
	v_lshlrev_b32_e32 v10, 16, v239
	v_and_b32_e32 v11, 0xffff0000, v239
	v_pk_fma_f32 v[90:91], v[234:235], s[4:5], v[8:9] op_sel_hi:[1,0,1]
	v_pk_fma_f32 v[92:93], v[232:233], s[4:5], v[86:87] op_sel_hi:[1,0,1]
	v_pk_fma_f32 v[86:87], v[230:231], s[4:5], v[10:11] op_sel_hi:[1,0,1]
	v_pk_fma_f32 v[88:89], v[228:229], s[4:5], v[88:89] op_sel_hi:[1,0,1]
	s_waitcnt vmcnt(0)
	v_lshlrev_b32_e32 v16, 16, v148
	v_and_b32_e32 v17, 0xffff0000, v148
	v_lshlrev_b32_e32 v10, 16, v149
	v_and_b32_e32 v11, 0xffff0000, v149
	v_pk_fma_f32 v[94:95], v[246:247], s[4:5], v[10:11] op_sel_hi:[1,0,1]
	v_pk_fma_f32 v[98:99], v[244:245], s[4:5], v[16:17] op_sel_hi:[1,0,1]
	v_mov_b32_e32 v0, v24
	v_mov_b32_e32 v1, v20
	v_mov_b32_e32 v2, v25
	v_mov_b32_e32 v3, v21
	v_pk_add_f32 v[0:1], v[0:1], v[2:3]
	v_mov_b32_e32 v2, v22
	v_mov_b32_e32 v3, v18
	v_pk_add_f32 v[0:1], v[2:3], v[0:1]
	v_mov_b32_e32 v2, v23
	v_mov_b32_e32 v3, v19
	v_pk_add_f32 v[0:1], v[2:3], v[0:1]
	v_lshlrev_b32_e32 v14, 16, v146
	v_and_b32_e32 v15, 0xffff0000, v146
	v_add_f32_e32 v1, 0, v1
	v_pk_fma_f32 v[100:101], v[248:249], s[4:5], v[14:15] op_sel_hi:[1,0,1]
	v_add_f32_e32 v4, v0, v1
	v_mov_b32_e32 v0, v46
	v_mov_b32_e32 v1, v48
	v_mov_b32_e32 v2, v47
	v_mov_b32_e32 v3, v49
	v_pk_add_f32 v[0:1], v[0:1], v[2:3]
	v_mov_b32_e32 v2, v42
	v_mov_b32_e32 v3, v44
	v_pk_add_f32 v[0:1], v[2:3], v[0:1]
	v_mov_b32_e32 v2, v43
	v_mov_b32_e32 v3, v45
	v_pk_add_f32 v[0:1], v[2:3], v[0:1]
	v_mov_b32_e32 v2, v69
	v_add_f32_e32 v1, v4, v1
	v_add_f32_e32 v0, v0, v1
	v_mov_b32_e32 v3, v73
	v_lshlrev_b32_e32 v8, 16, v147
	v_add_f32_dpp v0, v0, v0 quad_perm:[1,0,3,2] row_mask:0xf bank_mask:0xf bound_ctrl:1
	v_and_b32_e32 v9, 0xffff0000, v147
	v_pk_fma_f32 v[96:97], v[250:251], s[4:5], v[8:9] op_sel_hi:[1,0,1]
	v_add_f32_dpp v0, v0, v0 quad_perm:[2,3,0,1] row_mask:0xf bank_mask:0xf bound_ctrl:1
	s_nop 1
	v_add_f32_dpp v0, v0, v0 row_half_mirror row_mask:0xf bank_mask:0xf bound_ctrl:1
	s_nop 1
	v_add_f32_dpp v0, v0, v0 row_mirror row_mask:0xf bank_mask:0xf bound_ctrl:1
	s_nop 0
	v_readlane_b32 s2, v0, 16
	v_readlane_b32 s13, v0, 48
	v_readlane_b32 s0, v0, 0
	v_readlane_b32 s1, v0, 32
	v_mov_b32_e32 v0, s2
	v_mov_b32_e32 v1, s13
	v_pk_add_f32 v[0:1], s[0:1], v[0:1]
	s_nop 0
	v_add_f32_e32 v4, v0, v1
	v_mov_b32_e32 v0, v68
	v_mov_b32_e32 v1, v72
	v_pk_add_f32 v[0:1], v[0:1], v[2:3]
	v_mov_b32_e32 v2, v66
	v_mov_b32_e32 v3, v70
	v_pk_add_f32 v[0:1], v[2:3], v[0:1]
	v_mov_b32_e32 v2, v67
	v_mov_b32_e32 v3, v71
	v_pk_add_f32 v[0:1], v[2:3], v[0:1]
	v_mov_b32_e32 v2, v53
	v_add_f32_e32 v1, 0, v1
	v_add_f32_e32 v5, v0, v1
	v_mov_b32_e32 v0, v52
	v_mov_b32_e32 v1, v56
	v_mov_b32_e32 v3, v57
	v_pk_add_f32 v[0:1], v[0:1], v[2:3]
	v_mov_b32_e32 v2, v50
	v_mov_b32_e32 v3, v54
	v_pk_add_f32 v[0:1], v[2:3], v[0:1]
	v_mov_b32_e32 v2, v51
	v_mov_b32_e32 v3, v55
	v_pk_add_f32 v[0:1], v[2:3], v[0:1]
	v_mov_b32_e32 v2, v77
	v_add_f32_e32 v1, v5, v1
	v_add_f32_e32 v0, v0, v1
	v_mov_b32_e32 v3, v83
	v_fmamk_f32 v21, v4, 0xba800000, v21
	v_add_f32_dpp v0, v0, v0 quad_perm:[1,0,3,2] row_mask:0xf bank_mask:0xf bound_ctrl:1
	v_fmamk_f32 v25, v4, 0xba800000, v25
	v_fmac_f32_e32 v20, 0xba800000, v4
	v_add_f32_dpp v0, v0, v0 quad_perm:[2,3,0,1] row_mask:0xf bank_mask:0xf bound_ctrl:1
	v_fmac_f32_e32 v24, 0xba800000, v4
	v_fmac_f32_e32 v18, 0xba800000, v4
	v_add_f32_dpp v0, v0, v0 row_half_mirror row_mask:0xf bank_mask:0xf bound_ctrl:1
	v_fmac_f32_e32 v22, 0xba800000, v4
	v_fmamk_f32 v19, v4, 0xba800000, v19
	v_add_f32_dpp v0, v0, v0 row_mirror row_mask:0xf bank_mask:0xf bound_ctrl:1
	v_fmamk_f32 v23, v4, 0xba800000, v23
	v_readlane_b32 s2, v0, 16
	v_readlane_b32 s13, v0, 48
	v_readlane_b32 s0, v0, 0
	v_readlane_b32 s1, v0, 32
	v_mov_b32_e32 v0, s2
	v_mov_b32_e32 v1, s13
	v_pk_add_f32 v[0:1], s[0:1], v[0:1]
	v_fmamk_f32 v111, v4, 0xba800000, v49
	v_add_f32_e32 v5, v0, v1
	v_mov_b32_e32 v0, v76
	v_mov_b32_e32 v1, v82
	v_pk_add_f32 v[0:1], v[0:1], v[2:3]
	v_mov_b32_e32 v2, v74
	v_mov_b32_e32 v3, v78
	v_pk_add_f32 v[0:1], v[2:3], v[0:1]
	v_mov_b32_e32 v2, v75
	v_mov_b32_e32 v3, v79
	v_pk_add_f32 v[0:1], v[2:3], v[0:1]
	v_mov_b32_e32 v2, v61
	v_add_f32_e32 v1, 0, v1
	v_add_f32_e32 v6, v0, v1
	v_mov_b32_e32 v0, v60
	v_mov_b32_e32 v1, v64
	v_mov_b32_e32 v3, v65
	v_pk_add_f32 v[0:1], v[0:1], v[2:3]
	v_mov_b32_e32 v2, v58
	v_mov_b32_e32 v3, v62
	v_pk_add_f32 v[0:1], v[2:3], v[0:1]
	v_mov_b32_e32 v2, v59
	v_mov_b32_e32 v3, v63
	v_pk_add_f32 v[0:1], v[2:3], v[0:1]
	v_mov_b32_e32 v2, v89
	v_add_f32_e32 v1, v6, v1
	v_add_f32_e32 v0, v0, v1
	v_mov_b32_e32 v3, v93
	v_fmac_f32_e32 v48, 0xba800000, v4
	v_add_f32_dpp v0, v0, v0 quad_perm:[1,0,3,2] row_mask:0xf bank_mask:0xf bound_ctrl:1
	v_fmamk_f32 v110, v4, 0xba800000, v47
	v_fmac_f32_e32 v44, 0xba800000, v4
	v_add_f32_dpp v0, v0, v0 quad_perm:[2,3,0,1] row_mask:0xf bank_mask:0xf bound_ctrl:1
	v_fmac_f32_e32 v46, 0xba800000, v4
; __device__ __forceinline__ void phase_ln(const float* RES, const bf16_t* DEL, float* X, bf16_t* XB, const float* g, const float* b, bool write_xb) {
;     ...
;         for (int r = 0; r < 4; ++r) { float s = 0.f;
; #pragma unroll
;             for (int i = 0; i < 4; ++i) s += v[r][i][0] + v[r][i][1] + v[r][i][2] + v[r][i][3];
;             mean[r] = wave_sum(s) * (1.f / 1024.f); }
; #pragma unroll
;         for (int r = 0; r < 4; ++r) { float q = 0.f;
; #pragma unroll
;             for (int i = 0; i < 4; ++i) { v[r][i] -= mean[r]; q += v[r][i][0] * v[r][i][0] + v[r][i][1] * v[r][i][1] + v[r][i][2] * v[r][i][2] + v[r][i][3] * v[r][i][3]; }
;             rs[r] = rsqrtf(wave_sum(q) * (1.f / 1024.f) + 1e-5f); }
	v_mov_b32_e32 v47, v48
	v_add_f32_dpp v0, v0, v0 row_half_mirror row_mask:0xf bank_mask:0xf bound_ctrl:1
	v_fmamk_f32 v104, v4, 0xba800000, v43
	v_fmac_f32_e32 v42, 0xba800000, v4
	v_add_f32_dpp v0, v0, v0 row_mirror row_mask:0xf bank_mask:0xf bound_ctrl:1
	v_mov_b32_e32 v43, v44
	v_readlane_b32 s2, v0, 16
	v_readlane_b32 s13, v0, 48
	v_readlane_b32 s0, v0, 0
	v_readlane_b32 s1, v0, 32
	v_mov_b32_e32 v0, s2
	v_mov_b32_e32 v1, s13
	v_pk_add_f32 v[0:1], s[0:1], v[0:1]
	v_fmamk_f32 v105, v4, 0xba800000, v45
	v_add_f32_e32 v6, v0, v1
	v_mov_b32_e32 v0, v88
	v_mov_b32_e32 v1, v92
	v_pk_add_f32 v[0:1], v[0:1], v[2:3]
	v_mov_b32_e32 v2, v86
	v_mov_b32_e32 v3, v90
	v_pk_add_f32 v[0:1], v[2:3], v[0:1]
	v_mov_b32_e32 v2, v87
	v_mov_b32_e32 v3, v91
	v_pk_add_f32 v[0:1], v[2:3], v[0:1]
	v_mov_b32_e32 v2, v99
	v_add_f32_e32 v1, 0, v1
	v_add_f32_e32 v7, v0, v1
	v_mov_b32_e32 v0, v98
	v_mov_b32_e32 v1, v100
	v_mov_b32_e32 v3, v101
	v_pk_add_f32 v[0:1], v[0:1], v[2:3]
	v_mov_b32_e32 v2, v94
	v_mov_b32_e32 v3, v96
	v_pk_add_f32 v[0:1], v[2:3], v[0:1]
	v_mov_b32_e32 v2, v95
	v_mov_b32_e32 v3, v97
	v_pk_add_f32 v[0:1], v[2:3], v[0:1]
	v_mov_b32_e32 v2, v21
	v_add_f32_e32 v1, v7, v1
	v_add_f32_e32 v0, v0, v1
	v_mov_b32_e32 v3, v25
	v_pk_mul_f32 v[2:3], v[2:3], v[2:3]
	v_add_f32_dpp v0, v0, v0 quad_perm:[1,0,3,2] row_mask:0xf bank_mask:0xf bound_ctrl:1
	v_fmamk_f32 v128, v5, 0xba800000, v73
	v_fmamk_f32 v129, v5, 0xba800000, v69
	v_add_f32_dpp v0, v0, v0 quad_perm:[2,3,0,1] row_mask:0xf bank_mask:0xf bound_ctrl:1
	v_fmac_f32_e32 v68, 0xba800000, v5
	v_fmac_f32_e32 v72, 0xba800000, v5
	v_add_f32_dpp v0, v0, v0 row_half_mirror row_mask:0xf bank_mask:0xf bound_ctrl:1
	v_fmac_f32_e32 v66, 0xba800000, v5
	v_mov_b32_e32 v73, v68
	v_add_f32_dpp v0, v0, v0 row_mirror row_mask:0xf bank_mask:0xf bound_ctrl:1
	v_fmamk_f32 v109, v5, 0xba800000, v57
	v_readlane_b32 s2, v0, 16
	v_readlane_b32 s13, v0, 48
	v_readlane_b32 s0, v0, 0
	v_readlane_b32 s1, v0, 32
	v_mov_b32_e32 v0, s2
	v_mov_b32_e32 v1, s13
	v_pk_add_f32 v[0:1], s[0:1], v[0:1]
	v_fmac_f32_e32 v56, 0xba800000, v5
	v_add_f32_e32 v7, v0, v1
	v_mov_b32_e32 v0, v20
	v_mov_b32_e32 v1, v24
	v_pk_fma_f32 v[0:1], v[0:1], v[0:1], v[2:3]
	v_mov_b32_e32 v2, v18
	v_mov_b32_e32 v3, v22
	v_pk_fma_f32 v[0:1], v[2:3], v[2:3], v[0:1]
	v_mov_b32_e32 v2, v19
	v_mov_b32_e32 v3, v23
	v_pk_fma_f32 v[0:1], v[2:3], v[2:3], v[0:1]
	v_pk_mul_f32 v[2:3], v[110:111], v[110:111]
	v_add_f32_e32 v0, v0, v1
	v_pk_fma_f32 v[2:3], v[46:47], v[46:47], v[2:3]
	v_fmamk_f32 v108, v5, 0xba800000, v53
	v_pk_fma_f32 v[2:3], v[42:43], v[42:43], v[2:3]
	v_fmamk_f32 v122, v5, 0xba800000, v71
	v_pk_fma_f32 v[2:3], v[104:105], v[104:105], v[2:3]
	v_fmac_f32_e32 v70, 0xba800000, v5
	v_add_f32_e32 v0, v3, v0
	v_add_f32_e32 v0, v2, v0
	v_pk_mul_f32 v[2:3], v[128:129], v[128:129]
	v_fmamk_f32 v123, v5, 0xba800000, v67
	v_pk_fma_f32 v[2:3], v[72:73], v[72:73], v[2:3]
	v_mov_b32_e32 v71, v66
	v_fmamk_f32 v103, v5, 0xba800000, v55
	v_fmac_f32_e32 v54, 0xba800000, v5
	v_fmamk_f32 v102, v5, 0xba800000, v51
	v_fmac_f32_e32 v50, 0xba800000, v5
	v_fmac_f32_e32 v52, 0xba800000, v5
	v_mov_b32_e32 v53, v56
	v_pk_mul_f32 v[4:5], v[108:109], v[108:109]
	v_pk_fma_f32 v[2:3], v[70:71], v[70:71], v[2:3]
	v_pk_fma_f32 v[4:5], v[52:53], v[52:53], v[4:5]
	v_mov_b32_e32 v51, v54
	v_pk_fma_f32 v[2:3], v[122:123], v[122:123], v[2:3]
	v_pk_fma_f32 v[4:5], v[50:51], v[50:51], v[4:5]
	v_add_f32_e32 v2, v2, v3
	v_pk_fma_f32 v[4:5], v[102:103], v[102:103], v[4:5]
	v_add_f32_dpp v0, v0, v0 quad_perm:[1,0,3,2] row_mask:0xf bank_mask:0xf bound_ctrl:1
	v_add_f32_e32 v2, v5, v2
	v_add_f32_e32 v2, v4, v2
	v_add_f32_dpp v0, v0, v0 quad_perm:[2,3,0,1] row_mask:0xf bank_mask:0xf bound_ctrl:1
	v_fmamk_f32 v130, v6, 0xba800000, v83
	v_add_f32_dpp v2, v2, v2 quad_perm:[1,0,3,2] row_mask:0xf bank_mask:0xf bound_ctrl:1
	v_add_f32_dpp v0, v0, v0 row_half_mirror row_mask:0xf bank_mask:0xf bound_ctrl:1
	v_fmamk_f32 v131, v6, 0xba800000, v77
	v_add_f32_dpp v2, v2, v2 quad_perm:[2,3,0,1] row_mask:0xf bank_mask:0xf bound_ctrl:1
	v_add_f32_dpp v0, v0, v0 row_mirror row_mask:0xf bank_mask:0xf bound_ctrl:1
	v_fmac_f32_e32 v76, 0xba800000, v6
	v_add_f32_dpp v2, v2, v2 row_half_mirror row_mask:0xf bank_mask:0xf bound_ctrl:1
	v_readlane_b32 s2, v0, 16
	v_readlane_b32 s13, v0, 48
	v_add_f32_dpp v2, v2, v2 row_mirror row_mask:0xf bank_mask:0xf bound_ctrl:1
	v_readlane_b32 s0, v0, 0
	v_readlane_b32 s1, v0, 32
	v_mov_b32_e32 v0, s2
	v_mov_b32_e32 v1, s13
	v_readlane_b32 s2, v2, 16
	v_readlane_b32 s13, v2, 48
	v_pk_add_f32 v[0:1], s[0:1], v[0:1]
	v_readlane_b32 s0, v2, 0
	v_readlane_b32 s1, v2, 32
	v_mov_b32_e32 v2, s2
	v_mov_b32_e32 v3, s13
	v_pk_add_f32 v[2:3], s[0:1], v[2:3]
; __device__ __forceinline__ u32x4 pack8(const f32x4 a, const f32x4 b) { u32x4 w; w.x = pk_bf16(a[0], a[1]); w.y = pk_bf16(a[2], a[3]); w.z = pk_bf16(b[0], b[1]); w.w = pk_bf16(b[2], b[3]); return w; }
; __device__ __forceinline__ void phase_ln(const float* RES, const bf16_t* DEL, float* X, bf16_t* XB, const float* g, const float* b, bool write_xb) {
;     ...
;         for (int r = 0; r < 4; ++r) { float q = 0.f;
; #pragma unroll
;             for (int i = 0; i < 4; ++i) { v[r][i] -= mean[r]; q += v[r][i][0] * v[r][i][0] + v[r][i][1] * v[r][i][1] + v[r][i][2] * v[r][i][2] + v[r][i][3] * v[r][i][3]; }
;             rs[r] = rsqrtf(wave_sum(q) * (1.f / 1024.f) + 1e-5f); }
; #pragma unroll
;         for (int i = 0; i < 2; ++i) { const int c = i * 512 + lane * 8;
;             const f32x4 ga = *(const f32x4*)(g + c), gb = *(const f32x4*)(g + c + 4), ba = *(const f32x4*)(b + c), bb = *(const f32x4*)(b + c + 4);
; #pragma unroll
;             for (int r = 0; r < 4; ++r) { const size_t ro = (size_t)(base + r * nw) * 1024 + c;
;                 const f32x4 oa = v[r][2 * i] * rs[r] * ga + ba, ob = v[r][2 * i + 1] * rs[r] * gb + bb;
;                 *(f32x4*)(X + ro) = oa; *(f32x4*)(X + ro + 4) = ob;
;                 if (write_xb) *(u32x4*)(XB + ro) = pack8(oa, ob); } }
	v_mov_b32_e32 v5, v0
	v_mov_b32_e32 v4, v2
	v_mov_b32_e32 v0, v3
	v_pk_add_f32 v[0:1], v[4:5], v[0:1]
	v_fmac_f32_e32 v82, 0xba800000, v6
	v_pk_fma_f32 v[132:133], v[0:1], s[50:51], v[182:183] op_sel_hi:[1,0,0]
	v_fmac_f32_e32 v74, 0xba800000, v6
	v_mul_f32_e32 v0, 0x4b800000, v133
	v_cmp_gt_f32_e32 vcc, s8, v133
	v_mov_b32_e32 v83, v76
	v_fmamk_f32 v117, v6, 0xba800000, v65
	v_cndmask_b32_e32 v0, v133, v0, vcc
	v_rsq_f32_e32 v0, v0
	v_fmac_f32_e32 v64, 0xba800000, v6
	v_fmamk_f32 v116, v6, 0xba800000, v61
	v_fmamk_f32 v124, v6, 0xba800000, v79
	v_mul_f32_e32 v1, 0x45800000, v0
	v_cndmask_b32_e32 v118, v0, v1, vcc
	v_pk_mul_f32 v[0:1], v[130:131], v[130:131]
	v_fmac_f32_e32 v78, 0xba800000, v6
	v_pk_fma_f32 v[0:1], v[82:83], v[82:83], v[0:1]
	v_mov_b32_e32 v79, v74
	v_fmac_f32_e32 v62, 0xba800000, v6
	v_fmac_f32_e32 v60, 0xba800000, v6
	v_mov_b32_e32 v61, v64
	v_pk_mul_f32 v[2:3], v[116:117], v[116:117]
	v_fmamk_f32 v125, v6, 0xba800000, v75
	v_pk_fma_f32 v[0:1], v[78:79], v[78:79], v[0:1]
	v_fmamk_f32 v112, v6, 0xba800000, v59
	v_fmac_f32_e32 v58, 0xba800000, v6
	v_pk_fma_f32 v[2:3], v[60:61], v[60:61], v[2:3]
	v_mov_b32_e32 v59, v62
	v_pk_fma_f32 v[0:1], v[124:125], v[124:125], v[0:1]
	v_fmamk_f32 v113, v6, 0xba800000, v63
	v_pk_fma_f32 v[2:3], v[58:59], v[58:59], v[2:3]
	v_add_f32_e32 v0, v0, v1
	v_pk_fma_f32 v[2:3], v[112:113], v[112:113], v[2:3]
	v_fmamk_f32 v126, v7, 0xba800000, v93
	v_add_f32_e32 v0, v3, v0
	v_add_f32_e32 v0, v2, v0
	v_fmamk_f32 v127, v7, 0xba800000, v89
	v_fmac_f32_e32 v88, 0xba800000, v7
	v_add_f32_dpp v0, v0, v0 quad_perm:[1,0,3,2] row_mask:0xf bank_mask:0xf bound_ctrl:1
	v_fmac_f32_e32 v92, 0xba800000, v7
	v_fmac_f32_e32 v86, 0xba800000, v7
	v_add_f32_dpp v0, v0, v0 quad_perm:[2,3,0,1] row_mask:0xf bank_mask:0xf bound_ctrl:1
	v_mov_b32_e32 v93, v88
	v_fmamk_f32 v115, v7, 0xba800000, v101
	v_add_f32_dpp v0, v0, v0 row_half_mirror row_mask:0xf bank_mask:0xf bound_ctrl:1
	v_fmac_f32_e32 v100, 0xba800000, v7
	v_fmamk_f32 v114, v7, 0xba800000, v99
	v_add_f32_dpp v0, v0, v0 row_mirror row_mask:0xf bank_mask:0xf bound_ctrl:1
	v_fmamk_f32 v120, v7, 0xba800000, v91
	v_readlane_b32 s0, v0, 0
	v_readlane_b32 s2, v0, 16
	v_readlane_b32 s1, v0, 32
	v_readlane_b32 s13, v0, 48
	v_pk_mul_f32 v[0:1], v[126:127], v[126:127]
	v_fmac_f32_e32 v90, 0xba800000, v7
	v_pk_fma_f32 v[0:1], v[92:93], v[92:93], v[0:1]
	v_mov_b32_e32 v91, v86
	v_fmac_f32_e32 v96, 0xba800000, v7
	v_fmac_f32_e32 v98, 0xba800000, v7
	v_mov_b32_e32 v99, v100
	v_pk_mul_f32 v[2:3], v[114:115], v[114:115]
	v_fmamk_f32 v121, v7, 0xba800000, v87
	v_pk_fma_f32 v[0:1], v[90:91], v[90:91], v[0:1]
	v_fmamk_f32 v106, v7, 0xba800000, v95
	v_fmac_f32_e32 v94, 0xba800000, v7
	v_pk_fma_f32 v[2:3], v[98:99], v[98:99], v[2:3]
	v_mov_b32_e32 v95, v96
	v_pk_fma_f32 v[0:1], v[120:121], v[120:121], v[0:1]
	v_fmamk_f32 v107, v7, 0xba800000, v97
	v_pk_fma_f32 v[2:3], v[94:95], v[94:95], v[2:3]
	v_add_f32_e32 v0, v0, v1
	v_pk_fma_f32 v[2:3], v[106:107], v[106:107], v[2:3]
	v_pk_mul_f32 v[136:137], v[20:21], v[118:119] op_sel_hi:[1,0]
	v_add_f32_e32 v0, v3, v0
	v_add_f32_e32 v0, v2, v0
	v_pk_mul_f32 v[18:19], v[18:19], v[118:119] op_sel_hi:[1,0]
	v_pk_mul_f32 v[22:23], v[22:23], v[118:119] op_sel_hi:[1,0]
	v_add_f32_dpp v0, v0, v0 quad_perm:[1,0,3,2] row_mask:0xf bank_mask:0xf bound_ctrl:1
	v_cmp_gt_f32_e64 s[36:37], s8, v132
	s_andn2_b64 vcc, exec, s[42:43]
	v_add_f32_dpp v0, v0, v0 quad_perm:[2,3,0,1] row_mask:0xf bank_mask:0xf bound_ctrl:1
	s_nop 1
	v_add_f32_dpp v0, v0, v0 row_half_mirror row_mask:0xf bank_mask:0xf bound_ctrl:1
	s_nop 1
	v_add_f32_dpp v0, v0, v0 row_mirror row_mask:0xf bank_mask:0xf bound_ctrl:1
	s_nop 0
	v_readlane_b32 s46, v0, 0
	v_readlane_b32 s14, v0, 16
	v_readlane_b32 s47, v0, 32
	v_readlane_b32 s15, v0, 48
	global_load_dwordx4 v[0:3], v[30:31], off offset:16
	global_load_dwordx4 v[8:11], v[30:31], off
	global_load_dwordx4 v[4:7], v[32:33], off offset:16
	global_load_dwordx4 v[14:17], v[32:33], off
	s_waitcnt vmcnt(0)
	v_pk_fma_f32 v[20:21], v[18:19], v[10:11], v[16:17]
	v_pk_fma_f32 v[18:19], v[136:137], v[8:9], v[14:15]
	v_pk_mul_f32 v[136:137], v[24:25], v[118:119] op_sel_hi:[1,0]
	v_pk_fma_f32 v[24:25], v[22:23], v[2:3], v[6:7]
	v_pk_fma_f32 v[22:23], v[136:137], v[0:1], v[4:5]
	v_lshl_add_u64 v[136:137], v[134:135], 2, s[68:69]
	global_store_dwordx4 v[136:137], v[18:21], off
	global_store_dwordx4 v[136:137], v[22:25], off offset:16
	s_cbranch_vccnz .LBB0_222
	v_cvt_pk_bf16_f32 v18, v18, v19
	v_cvt_pk_bf16_f32 v19, v20, v21
	v_cvt_pk_bf16_f32 v20, v22, v23
	v_cvt_pk_bf16_f32 v21, v24, v25
	v_lshl_add_u64 v[22:23], v[134:135], 1, s[72:73]
	global_store_dwordx4 v[22:23], v[18:21], off

; #define LAS __attribute__((address_space(3)))
; __device__ __forceinline__ unsigned pk_bf16(float lo, float hi) { const f32x2_t f = {lo, hi}; return __builtin_bit_cast(unsigned, __builtin_convertvector(f, bf16x2_t)); }
; __device__ __forceinline__ int otid() { int t = threadIdx.x; asm volatile("" : "+v"(t)); return t; }
; __device__ __forceinline__ int obid() { int b = blockIdx.x; asm volatile("" : "+s"(b)); return b; }
; __device__ __forceinline__ void wtrans(const float* __restrict__ src, int K, int N, bf16_t* __restrict__ dst, int ldd, int mode, LAS float* tile) {
;     const int tid = otid(), tn = N >> 6, nt = (K >> 6) * tn;
;     for (int t = obid(); t < nt; t += gridDim.x) {
;         const int k0 = (t / tn) << 6, c0 = (t % tn) << 6;
;         {
; #pragma unroll
;           for (int i = 0; i < 2; ++i) { const int e = tid + 512 * i, kl = e >> 4, c4 = (e & 15) * 4;
;               const f32x4 v4 = *(const f32x4*)(src + (size_t)(k0 + kl) * N + c0 + c4);
;               tile[kl * 65 + c4] = v4[0]; tile[kl * 65 + c4 + 1] = v4[1]; tile[kl * 65 + c4 + 2] = v4[2]; tile[kl * 65 + c4 + 3] = v4[3]; } }
;         __syncthreads();
;         { const int kp = tid & 31, cl0 = tid >> 5;
; #pragma unroll
;           for (int i = 0; i < 4; ++i) { const int cl = cl0 + 16 * i, c = c0 + cl; const int R = mode ? gu_row(c) : c;
;               *(unsigned*)(dst + (size_t)R * ldd + k0 + 2 * kp) = pk_bf16(tile[(2 * kp) * 65 + cl], tile[(2 * kp + 1) * 65 + cl]); } }
.Lwpb_entry:
	v_and_b32_e32 v1, 63, v183
	v_lshrrev_b32_e32 v15, 6, v183
	s_nop 0
	v_readfirstlane_b32 s87, v15
	s_lshl_b32 s13, s5, 3
	s_add_u32 s13, s13, s87
	s_mul_i32 s87, s87, 8448
	v_lshrrev_b32_e32 v10, 4, v1
	v_and_b32_e32 v11, 15, v1
	v_mul_u32_u24_e32 v2, 528, v11
	v_lshl_add_u32 v2, v10, 2, v2
	v_add_u32_e32 v2, s87, v2
	v_lshlrev_b32_e32 v10, 1, v10
	v_lshlrev_b32_e32 v11, 4, v11
	v_lshrrev_b32_e32 v13, 5, v1
	v_and_b32_e32 v14, 31, v1
	v_lshlrev_b32_e32 v14, 2, v14
	v_mul_u32_u24_e32 v4, 132, v13
	v_add_u32_e32 v4, v4, v14
	v_add_u32_e32 v4, s87, v4
	v_readlane_b32 s0, v252, 0
	v_readlane_b32 s1, v252, 1
	s_sub_u32 s0, s0, 0xe0
	s_subb_u32 s1, s1, 0

; #define LAS __attribute__((address_space(3)))
; __device__ __forceinline__ void phase_wprep(const Params& p, int l, LAS float* tile) {
;     bf16_t* WB = (bf16_t*)(p.ws + WS_WB);
;     wtrans(p.in[1] + (size_t)(l * 2 + 0) * 1024 * 5632, 1024, 5632, WB + WB_GU0, 1024, 1, tile);
;     wtrans(p.in[1] + (size_t)(l * 2 + 1) * 1024 * 5632, 1024, 5632, WB + WB_GU1, 1024, 1, tile);
;     wtrans(p.in[2] + (size_t)(l * 2 + 0) * 2816 * 1024, 2816, 1024, WB + WB_D0, 2816, 0, tile);
;     wtrans(p.in[2] + (size_t)(l * 2 + 1) * 2816 * 1024, 2816, 1024, WB + WB_D1, 2816, 0, tile);
;     wtrans(p.in[5] + (size_t)l * 1024 * 4608, 1024, 4608, WB + WB_IN, 1024, 0, tile);
;     wtrans(p.in[23] + (size_t)l * 512 * 1024, 512, 1024, WB + WB_BA, 512, 0, tile);
;     wtrans(p.in[24] + (size_t)l * 512 * 1024, 512, 1024, WB + WB_BB, 512, 0, tile);
;     wtrans(p.in[25] + (size_t)l * 1024 * 1024, 1024, 1024, WB + WB_O, 1024, 0, tile);
.Lwpb_m0:
	s_sub_u32 s25, s13, 0
	s_mul_hi_u32 s32, s25, 0x2e8ba2f
	s_mul_i32 s87, s32, 88
	s_sub_u32 s50, s25, s87
	s_load_dwordx2 s[14:15], s[0:1], 0x8
	s_waitcnt lgkmcnt(0)
	s_mul_i32 s87, s32, 1441792
	s_lshl_b32 s88, s50, 8
	s_add_u32 s87, s87, s88
	s_add_u32 s14, s14, 0x2c00000
	s_addc_u32 s15, s15, 0
	s_add_u32 s14, s14, s87
	s_addc_u32 s15, s15, 0
	s_mov_b32 s52, 22528
	s_mov_b32 s53, 180224
	s_mov_b32 s80, 2048
	s_cmp_ge_u32 s50, 44
	s_cselect_b32 s87, 1, 0
	s_mul_i32 s88, s87, 44
	s_sub_u32 s88, s50, s88
	s_lshl_b32 s86, s87, 4
	s_and_b32 s87, s88, 1
	s_lshl_b32 s87, s87, 6
	s_add_u32 s86, s86, s87
	s_lshr_b32 s88, s88, 1
	s_lshl_b32 s88, s88, 8
	s_add_u32 s86, s86, s88
	s_mul_i32 s87, s86, 2048
	s_lshl_b32 s88, s32, 7
	s_add_u32 s87, s87, s88
	s_add_u32 s87, s87, 0x0
	s_add_u32 s36, s70, s87
	s_addc_u32 s37, s71, 0
	s_branch .Lwpb_body1
.Lwpb_m1:
	s_sub_u32 s25, s13, 1408
	s_mul_hi_u32 s32, s25, 0x2e8ba2f
	s_mul_i32 s87, s32, 88
	s_sub_u32 s50, s25, s87
	s_load_dwordx2 s[14:15], s[0:1], 0x8
	s_waitcnt lgkmcnt(0)
	s_mul_i32 s87, s32, 1441792
	s_lshl_b32 s88, s50, 8
	s_add_u32 s87, s87, s88
	s_add_u32 s14, s14, 0x4200000
	s_addc_u32 s15, s15, 0
	s_add_u32 s14, s14, s87
	s_addc_u32 s15, s15, 0
	s_mov_b32 s52, 22528
	s_mov_b32 s53, 180224
	s_mov_b32 s80, 2048
	s_cmp_ge_u32 s50, 44
	s_cselect_b32 s87, 1, 0
	s_mul_i32 s88, s87, 44
	s_sub_u32 s88, s50, s88
	s_lshl_b32 s86, s87, 4
	s_and_b32 s87, s88, 1
	s_lshl_b32 s87, s87, 6
	s_add_u32 s86, s86, s87
	s_lshr_b32 s88, s88, 1
	s_lshl_b32 s88, s88, 8
	s_add_u32 s86, s86, s88
	s_mul_i32 s87, s86, 2048
	s_lshl_b32 s88, s32, 7
	s_add_u32 s87, s87, s88
	s_add_u32 s87, s87, 0xb00000
	s_add_u32 s36, s70, s87
	s_addc_u32 s37, s71, 0
	s_branch .Lwpb_body1
.Lwpb_m2:
	s_sub_u32 s25, s13, 2816
	s_lshr_b32 s32, s25, 4
	s_and_b32 s50, s25, 15
	s_load_dwordx2 s[14:15], s[0:1], 0x10
	s_waitcnt lgkmcnt(0)
	s_mul_i32 s87, s32, 262144
	s_lshl_b32 s88, s50, 8
	s_add_u32 s87, s87, s88
	s_add_u32 s14, s14, 0x1600000
	s_addc_u32 s15, s15, 0
	s_add_u32 s14, s14, s87
	s_addc_u32 s15, s15, 0
	s_mov_b32 s52, 4096
	s_mov_b32 s53, 32768
	s_mov_b32 s80, 5632
	s_lshl_b32 s86, s50, 6
	s_mul_i32 s87, s86, 5632
	s_lshl_b32 s88, s32, 7
	s_add_u32 s87, s87, s88
	s_add_u32 s87, s87, 0x1600000
	s_add_u32 s36, s70, s87
	s_addc_u32 s37, s71, 0
	s_branch .Lwpb_body0
.Lwpb_m3:
	s_sub_u32 s25, s13, 3520
	s_lshr_b32 s32, s25, 4
	s_and_b32 s50, s25, 15
	s_load_dwordx2 s[14:15], s[0:1], 0x10
	s_waitcnt lgkmcnt(0)
	s_mul_i32 s87, s32, 262144
	s_lshl_b32 s88, s50, 8
	s_add_u32 s87, s87, s88
	s_add_u32 s14, s14, 0x2100000
	s_addc_u32 s15, s15, 0
	s_add_u32 s14, s14, s87
	s_addc_u32 s15, s15, 0
	s_mov_b32 s52, 4096
	s_mov_b32 s53, 32768
	s_mov_b32 s80, 5632
	s_lshl_b32 s86, s50, 6
	s_mul_i32 s87, s86, 5632
	s_lshl_b32 s88, s32, 7
	s_add_u32 s87, s87, s88
	s_add_u32 s87, s87, 0x1b80000
	s_add_u32 s36, s70, s87
	s_addc_u32 s37, s71, 0
	s_branch .Lwpb_body0
.Lwpb_m4:
	s_sub_u32 s25, s13, 4224
	s_mul_hi_u32 s32, s25, 0x38e38e4
	s_mul_i32 s87, s32, 72
	s_sub_u32 s50, s25, s87
	s_load_dwordx2 s[14:15], s[0:1], 0x28
	s_waitcnt lgkmcnt(0)
	s_mul_i32 s87, s32, 1179648
	s_lshl_b32 s88, s50, 8
	s_add_u32 s87, s87, s88
	s_add_u32 s14, s14, 0x1200000
	s_addc_u32 s15, s15, 0
	s_add_u32 s14, s14, s87
	s_addc_u32 s15, s15, 0
	s_mov_b32 s52, 18432
	s_mov_b32 s53, 147456
	s_mov_b32 s80, 2048
	s_lshl_b32 s86, s50, 6
	s_mul_i32 s87, s86, 2048
	s_lshl_b32 s88, s32, 7
	s_add_u32 s87, s87, s88
	s_add_u32 s87, s87, 0x2100000
	s_add_u32 s36, s70, s87
	s_addc_u32 s37, s71, 0
	s_branch .Lwpb_body0
.Lwpb_m5:
	s_sub_u32 s25, s13, 5376
	s_lshr_b32 s32, s25, 4
	s_and_b32 s50, s25, 15
	s_load_dwordx2 s[14:15], s[0:1], 0xb8
	s_waitcnt lgkmcnt(0)
	s_mul_i32 s87, s32, 262144
	s_lshl_b32 s88, s50, 8
	s_add_u32 s87, s87, s88
	s_add_u32 s14, s14, 0x200000
	s_addc_u32 s15, s15, 0
	s_add_u32 s14, s14, s87
	s_addc_u32 s15, s15, 0
	s_mov_b32 s52, 4096
	s_mov_b32 s53, 32768
	s_mov_b32 s80, 1024
	s_lshl_b32 s86, s50, 6
	s_mul_i32 s87, s86, 1024
	s_lshl_b32 s88, s32, 7
	s_add_u32 s87, s87, s88
	s_add_u32 s87, s87, 0x2a00000
	s_add_u32 s36, s70, s87
	s_addc_u32 s37, s71, 0
	s_branch .Lwpb_body0
.Lwpb_m6:
	s_sub_u32 s25, s13, 5504
	s_lshr_b32 s32, s25, 4
	s_and_b32 s50, s25, 15
	v_readlane_b32 s14, v252, 54
	v_readlane_b32 s15, v252, 55
	s_mul_i32 s87, s32, 262144
	s_lshl_b32 s88, s50, 8
	s_add_u32 s87, s87, s88
	s_add_u32 s14, s14, 0x200000
	s_addc_u32 s15, s15, 0
	s_add_u32 s14, s14, s87
	s_addc_u32 s15, s15, 0
	s_mov_b32 s52, 4096
	s_mov_b32 s53, 32768
	s_mov_b32 s80, 1024
	s_lshl_b32 s86, s50, 6
	s_mul_i32 s87, s86, 1024
	s_lshl_b32 s88, s32, 7
	s_add_u32 s87, s87, s88
	s_add_u32 s87, s87, 0x2b00000
	s_add_u32 s36, s70, s87
	s_addc_u32 s37, s71, 0
	s_branch .Lwpb_body0
.Lwpb_m7:
	s_sub_u32 s25, s13, 5632
	s_lshr_b32 s32, s25, 4
	s_and_b32 s50, s25, 15
	v_readlane_b32 s14, v252, 56
	v_readlane_b32 s15, v252, 57
	s_mul_i32 s87, s32, 262144
	s_lshl_b32 s88, s50, 8
	s_add_u32 s87, s87, s88
	s_add_u32 s14, s14, 0x400000
	s_addc_u32 s15, s15, 0
	s_add_u32 s14, s14, s87
	s_addc_u32 s15, s15, 0
	s_mov_b32 s52, 4096
	s_mov_b32 s53, 32768
	s_mov_b32 s80, 2048
	s_lshl_b32 s86, s50, 6
	s_mul_i32 s87, s86, 2048
	s_lshl_b32 s88, s32, 7
	s_add_u32 s87, s87, s88
	s_add_u32 s87, s87, 0x2c00000
	s_add_u32 s36, s70, s87
	s_addc_u32 s37, s71, 0
	s_branch .Lwpb_body0

; #define LAS __attribute__((address_space(3)))
; __device__ __forceinline__ int otid() { int t = threadIdx.x; asm volatile("" : "+v"(t)); return t; }
; __device__ __forceinline__ int obid() { int b = blockIdx.x; asm volatile("" : "+s"(b)); return b; }
; __device__ __forceinline__ void phase_scan2(const Params& p, int l, LAS unsigned char* lds) {
;     unsigned char* R = p.ws + WS_R;
;     const bf16_t* Rb = (const bf16_t*)(R + R_R); const bf16_t* Kb = (const bf16_t*)(R + R_K); const bf16_t* Vb = (const bf16_t*)(R + (l == 0 ? R_V : R_VNEW));
;     const bf16_t* Ab = (const bf16_t*)(R + R_A); const _Float16* EW = (const _Float16*)(R + R_EW);
;     bf16_t* Y = (bf16_t*)(R + R_Y); float* CB = (float*)(R + R_CB);
;     const float* k_k = p.in[15] + (size_t)l * 512; const float* k_a = p.in[16] + (size_t)l * 512; const float* r_k = p.in[17] + (size_t)l * 512;
;     const int tid = otid(), wid = tid >> 6, lane = tid & 63, fr = lane & 15, fq = lane >> 4;
;     constexpr int NCH = SEQ / 16, NRD = (NCH + SC_NP - 1) / SC_NP;
;     for (int job = obid(); job < 256; job += gridDim.x) {
;         const int bh = job >> 2, rg = job & 3, b = bh >> 3, h = bh & 7;
;         const size_t tok0 = (size_t)b * SEQ;
;         const int pw = wid - 3, j = lane;
;         const float kkc = k_k[h * 64 + j], kac = k_a[h * 64 + j], rkc = r_k[h * 64 + j];
.Lsc_entry:
	v_lshrrev_b32_e32 v4, 6, v183
	v_and_b32_e32 v1, 15, v183
	v_readfirstlane_b32 s25, v4
	s_add_u32 s26, s74, 0xc000000
	s_addc_u32 s27, s75, 0
	v_bfe_u32 v2, v183, 4, 2
	v_lshrrev_b32_e32 v4, 2, v1
	v_and_b32_e32 v7, 3, v1
	s_add_u32 s36, s74, 0x13000000
	s_addc_u32 s37, s75, 0
	v_lshlrev_b32_e32 v6, 5, v1
	v_lshl_add_u32 v4, v2, 2, v4
	v_lshlrev_b32_e32 v7, 3, v7
	s_add_u32 s38, s74, 0xa000000
	s_addc_u32 s39, s75, 0
	v_and_b32_e32 v0, 63, v183
	v_lshl_add_u32 v6, v2, 3, v6
	v_lshl_add_u32 v7, v4, 5, v7
	s_add_u32 s46, s74, 0x11000000
	s_mov_b32 s13, s5
	s_addc_u32 s47, s75, 0

; #define LAS __attribute__((address_space(3)))
; __device__ __forceinline__ float bf2f(bf16_t b) { return __uint_as_float(((unsigned)b) << 16); }
; __device__ __forceinline__ bf16_t bf1(float x) { return (bf16_t)(pk_bf16(x, 0.f) & 0xffffu); }
; __device__ __forceinline__ void phase_scan2(const Params& p, int l, LAS unsigned char* lds) {
;     ...
;         const int pw = wid - 3, j = lane;
;         const float kkc = k_k[h * 64 + j], kac = k_a[h * 64 + j], rkc = r_k[h * 64 + j];
;         unsigned short kraw[16], araw[16], rraw[16]; _Float16 eraw[16]; unsigned short vraw[4];
; #pragma unroll
;         for (int t = 0; t < 16; ++t) { kraw[t] = 0; araw[t] = 0; rraw[t] = 0; eraw[t] = (_Float16)0; }
; #pragma unroll
;         for (int q = 0; q < 4; ++q) vraw[q] = 0;
;         auto pload = [&](int c) {
;             const size_t base = (tok0 + (size_t)c * 16) * 512 + h * 64;
; #pragma unroll
;             for (int t = 0; t < 16; ++t) { const size_t off = base + (size_t)t * 512 + j; kraw[t] = Kb[off]; araw[t] = Ab[off]; rraw[t] = Rb[off]; eraw[t] = EW[off]; }
; #pragma unroll
;             for (int q = 0; q < 4; ++q) vraw[q] = Vb[base + (size_t)(4 * fq + q) * 512 + rg * 16 + fr];
;         };
;         auto pbuild = [&](int c, LAS unsigned char* sl, LAS unsigned char* sc, int cnext) {
;             float W = 1.f;
;             const int m = j >> 5, tp = (j >> 4) & 1, jw = j & 15, pidx = (jw >> 2) * 8 + tp * 4 + (jw & 3);
; #pragma unroll
;             for (int t = 0; t < 16; ++t) {
;                 const float k = bf2f(kraw[t]), a = bf2f(araw[t]), r = bf2f(rraw[t]);
;                 const float q = k * kkc, kp1 = k * (1.f + (a - 1.f) * kac);
;                 *(LAS bf16_t*)(sc + 0 + (t * 64 + j) * 2) = bf1(q * q);
;                 *(LAS bf16_t*)(sc + 2048 + (t * 64 + j) * 2) = bf1(r * kp1 * rkc);
.Lsc_producer:
	s_sub_u32 s55, s25, 1
	s_cmp_gt_u32 s25, 4
	s_cselect_b32 s0, 1, 0
	s_sub_u32 s55, s55, s0
	s_cmp_gt_u32 s25, 4
	s_cbranch_scc0 .Lsc_p_noprio
	s_setprio 1
.Lsc_p_noprio:
	v_cmp_eq_u32_e32 vcc, 0, v1
	v_lshl_add_u32 v4, v2, 2, 0
	s_nop 0
	v_cndmask_b32_e64 v21, 0, 1.0, vcc
	v_cmp_eq_u32_e32 vcc, v4, v1
	s_lshl_b32 s0, s52, 8
	s_nop 0
	v_cndmask_b32_e64 v26, 0, 1.0, vcc
	v_cmp_gt_u32_e32 vcc, v4, v1
	v_readlane_b32 s14, v243, 51
	s_nop 0
	v_cndmask_b32_e64 v34, 0, 1.0, vcc
	v_cmp_ge_u32_e32 vcc, v4, v1
	v_lshl_add_u32 v4, v2, 2, 1
	s_nop 0
	v_cndmask_b32_e64 v38, 0, 1.0, vcc
	v_cmp_eq_u32_e32 vcc, v4, v1
	v_readlane_b32 s15, v243, 52
	s_nop 0
	v_cndmask_b32_e64 v27, 0, 1.0, vcc
	v_cmp_gt_u32_e32 vcc, v4, v1
	s_lshl_b64 s[14:15], s[14:15], 2
	s_nop 0
	v_cndmask_b32_e64 v35, 0, 1.0, vcc
	v_cmp_ge_u32_e32 vcc, v4, v1
	v_lshl_add_u32 v4, v2, 2, 2
	s_nop 0
	v_cndmask_b32_e64 v39, 0, 1.0, vcc
	v_cmp_eq_u32_e32 vcc, v4, v1
	v_readlane_b32 s1, v252, 37
	s_nop 0
	v_cndmask_b32_e64 v32, 0, 1.0, vcc
	v_cmp_gt_u32_e32 vcc, v4, v1
	v_and_b32_e32 v5, 7, v1
	s_nop 0
	v_cndmask_b32_e64 v36, 0, 1.0, vcc
	v_cmp_ge_u32_e32 vcc, v4, v1
	v_lshl_add_u32 v4, v2, 2, 3
	s_nop 0
	v_cndmask_b32_e64 v40, 0, 1.0, vcc
	v_cmp_eq_u32_e32 vcc, v4, v1
	v_lshlrev_b32_e32 v16, 6, v2
	s_nop 0
	v_cndmask_b32_e64 v33, 0, 1.0, vcc
	v_cmp_gt_u32_e32 vcc, v4, v1
	v_mov_b32_e32 v22, 1.0
	s_nop 0
	v_cndmask_b32_e64 v37, 0, 1.0, vcc
	v_cmp_ge_u32_e32 vcc, v4, v1
	v_lshl_add_u32 v4, v0, 2, s0
	v_readlane_b32 s0, v252, 36
	v_mov_b32_e32 v23, 1.0
	s_add_u32 s0, s0, s14
	s_addc_u32 s1, s1, s15
	global_load_dword v76, v4, s[0:1]
	v_readlane_b32 s0, v252, 38
	v_readlane_b32 s1, v252, 39
	s_add_u32 s0, s0, s14
	s_addc_u32 s1, s1, s15
	global_load_dword v80, v4, s[0:1]
	v_readlane_b32 s0, v252, 40
	v_readlane_b32 s1, v252, 41
	s_add_u32 s0, s0, s14
	s_addc_u32 s1, s1, s15
	global_load_dword v248, v4, s[0:1]
	s_mul_i32 s0, s54, 4096
	s_lshl_b32 s1, s55, 4
	s_add_u32 s1, s1, s0
	v_add_u32_e32 v8, s1, v1
	s_lshl_b32 s14, s52, 7
	v_lshlrev_b32_e32 v8, 10, v8
	v_lshl_add_u32 v4, v2, 5, s14
	v_lshl_add_u32 v9, v2, 2, s1
	v_add_u32_e32 v8, v8, v4
	s_lshl_b32 s15, s53, 5
	s_add_u32 s14, s14, s15
	v_lshlrev_b32_e32 v9, 10, v9
	v_lshl_add_u32 v4, v1, 1, s14
	s_mul_i32 s0, s55, 2816
	v_add_u32_e32 v9, v9, v4
	v_lshlrev_b32_e32 v4, 1, v2
	s_add_u32 s0, s0, 132096
	v_xor_b32_e32 v4, v4, v5
	v_mov_b32_e32 v24, 0xbfb8aa3b
	v_lshlrev_b32_e32 v4, 4, v4
	v_mov_b32_e32 v25, 0xbfb8aa3b
	v_lshl_add_u32 v11, v1, 7, v4
	v_mov_b32_e32 v28, 0x3f803f80
	v_mov_b32_e32 v29, 0x3f803f80
	v_mov_b32_e32 v30, 0x3f803f80
	v_mov_b32_e32 v31, 0x3f803f80
	v_cndmask_b32_e64 v41, 0, 1.0, vcc
	v_lshlrev_b32_e32 v10, 5, v1
	v_xor_b32_e32 v13, 16, v11
	v_add_u32_e32 v16, 10752, v16
	v_add_u32_e32 v14, s0, v7
	v_add_u32_e32 v15, s0, v6
	v_lshl_add_u32 v4, v0, 2, s0
	s_waitcnt vmcnt(0)
	ds_write_b32 v4, v76 offset:2048
	ds_write_b32 v4, v80 offset:2304
	ds_write_b32 v4, v248 offset:2560
	global_load_dwordx4 v[44:47], v8, s[26:27]
	global_load_dwordx4 v[48:51], v8, s[26:27] offset:16
	global_load_dwordx4 v[52:55], v8, s[36:37]
	global_load_dwordx4 v[56:59], v8, s[36:37] offset:16
	global_load_dwordx4 v[60:63], v8, s[38:39]
	global_load_dwordx4 v[64:67], v8, s[38:39] offset:16
	v_lshl_add_u32 v42, v2, 6, s0
	global_load_dwordx4 v[68:71], v8, s[46:47]
	global_load_dwordx4 v[72:75], v8, s[46:47] offset:16
	s_lshl_b32 s0, s1, 5
	global_load_ushort v84, v9, s[60:61] offset:0
	s_lshl_b32 s14, s52, 2
	global_load_ushort v85, v9, s[60:61] offset:1024
	s_add_u32 s0, s0, s14
	global_load_ushort v86, v9, s[60:61] offset:2048
	s_add_u32 s0, s0, 0x9000000
	global_load_ushort v87, v9, s[60:61] offset:3072
	s_add_u32 s50, s74, s0
	v_add_u32_e32 v8, 0x18000, v8
	v_add_u32_e32 v9, 0x18000, v9
	s_mul_i32 s57, s55, 11008
	s_mov_b32 s56, 0
	s_addc_u32 s51, s75, 0
	s_mov_b32 s58, s55
	s_mov_b32 s42, 0
.Lsc_p_loop:
	s_cmp_ge_u32 s58, 256
	s_cbranch_scc1 .Lsc_p_skip
	s_add_u32 s0, s57, s56
	v_add_u32_e32 v17, s0, v11
	v_add_u32_e32 v18, s0, v13
	v_add_u32_e32 v19, s0, v6
	v_add_u32_e32 v20, s0, v16
	s_waitcnt vmcnt(0)
	v_lshl_or_b32 v76, v85, 16, v84
	v_lshl_or_b32 v77, v87, 16, v86
	v_and_b32_e32 v89, 0xffff0000, v44
	v_lshlrev_b32_e32 v88, 16, v44
	v_and_b32_e32 v105, 0xffff0000, v52
	v_lshlrev_b32_e32 v104, 16, v52
	v_and_b32_e32 v121, 0xffff0000, v60
	v_lshlrev_b32_e32 v120, 16, v60
	v_cvt_f32_f16_sdwa v153, v68 dst_sel:DWORD dst_unused:UNUSED_PAD src0_sel:WORD_1
	v_cvt_f32_f16_e32 v152, v68
	v_and_b32_e32 v91, 0xffff0000, v45
	v_lshlrev_b32_e32 v90, 16, v45
	v_and_b32_e32 v107, 0xffff0000, v53
	v_lshlrev_b32_e32 v106, 16, v53
	v_and_b32_e32 v123, 0xffff0000, v61
	v_lshlrev_b32_e32 v122, 16, v61
	v_cvt_f32_f16_sdwa v155, v69 dst_sel:DWORD dst_unused:UNUSED_PAD src0_sel:WORD_1
	v_cvt_f32_f16_e32 v154, v69
	v_and_b32_e32 v93, 0xffff0000, v46
	v_lshlrev_b32_e32 v92, 16, v46
	v_and_b32_e32 v109, 0xffff0000, v54
	v_lshlrev_b32_e32 v108, 16, v54
	v_and_b32_e32 v125, 0xffff0000, v62
	v_lshlrev_b32_e32 v124, 16, v62
	v_cvt_f32_f16_sdwa v157, v70 dst_sel:DWORD dst_unused:UNUSED_PAD src0_sel:WORD_1
	v_cvt_f32_f16_e32 v156, v70
	v_and_b32_e32 v95, 0xffff0000, v47
	v_lshlrev_b32_e32 v94, 16, v47
	v_and_b32_e32 v111, 0xffff0000, v55
	v_lshlrev_b32_e32 v110, 16, v55
	v_and_b32_e32 v127, 0xffff0000, v63
	v_lshlrev_b32_e32 v126, 16, v63
	v_cvt_f32_f16_sdwa v159, v71 dst_sel:DWORD dst_unused:UNUSED_PAD src0_sel:WORD_1
	v_cvt_f32_f16_e32 v158, v71
	v_and_b32_e32 v97, 0xffff0000, v48
	v_lshlrev_b32_e32 v96, 16, v48
	v_and_b32_e32 v113, 0xffff0000, v56
	v_lshlrev_b32_e32 v112, 16, v56
	v_and_b32_e32 v129, 0xffff0000, v64
	v_lshlrev_b32_e32 v128, 16, v64
	v_cvt_f32_f16_sdwa v161, v72 dst_sel:DWORD dst_unused:UNUSED_PAD src0_sel:WORD_1
	v_cvt_f32_f16_e32 v160, v72
	v_and_b32_e32 v99, 0xffff0000, v49
	v_lshlrev_b32_e32 v98, 16, v49
	v_and_b32_e32 v115, 0xffff0000, v57
	v_lshlrev_b32_e32 v114, 16, v57
	v_and_b32_e32 v131, 0xffff0000, v65
	v_lshlrev_b32_e32 v130, 16, v65
	v_cvt_f32_f16_sdwa v163, v73 dst_sel:DWORD dst_unused:UNUSED_PAD src0_sel:WORD_1
	v_cvt_f32_f16_e32 v162, v73
	v_and_b32_e32 v101, 0xffff0000, v50
	v_lshlrev_b32_e32 v100, 16, v50
	v_and_b32_e32 v117, 0xffff0000, v58
	v_lshlrev_b32_e32 v116, 16, v58
	v_and_b32_e32 v133, 0xffff0000, v66
	v_lshlrev_b32_e32 v132, 16, v66
	v_cvt_f32_f16_sdwa v165, v74 dst_sel:DWORD dst_unused:UNUSED_PAD src0_sel:WORD_1
	v_cvt_f32_f16_e32 v164, v74
	v_and_b32_e32 v103, 0xffff0000, v51
	v_lshlrev_b32_e32 v102, 16, v51
	v_and_b32_e32 v119, 0xffff0000, v59
	v_lshlrev_b32_e32 v118, 16, v59
	v_and_b32_e32 v135, 0xffff0000, v67
	v_lshlrev_b32_e32 v134, 16, v67
	v_cvt_f32_f16_sdwa v167, v75 dst_sel:DWORD dst_unused:UNUSED_PAD src0_sel:WORD_1
	v_cvt_f32_f16_e32 v166, v75
	s_add_u32 s0, s58, 6
	ds_write_b64 v19, v[76:77] offset:10240
	s_cmp_ge_u32 s0, 256
	s_cbranch_scc1 .Lsc_p_nopf
; #define LAS __attribute__((address_space(3)))
; __device__ __forceinline__ float bf2f(bf16_t b) { return __uint_as_float(((unsigned)b) << 16); }
; __device__ __forceinline__ bf16_t bf1(float x) { return (bf16_t)(pk_bf16(x, 0.f) & 0xffffu); }
; __device__ __forceinline__ void phase_scan2(const Params& p, int l, LAS unsigned char* lds) {
;     ...
;                 const float k = bf2f(kraw[t]), a = bf2f(araw[t]), r = bf2f(rraw[t]);
;                 const float q = k * kkc, kp1 = k * (1.f + (a - 1.f) * kac);
;                 *(LAS bf16_t*)(sc + 0 + (t * 64 + j) * 2) = bf1(q * q);
;                 *(LAS bf16_t*)(sc + 2048 + (t * 64 + j) * 2) = bf1(r * kp1 * rkc);
;             }
;             asm volatile("s_waitcnt lgkmcnt(0)" ::: "memory");
;             { const bf16x8 ones = __builtin_bit_cast(bf16x8, (u32x4){0x3F803F80u, 0x3F803F80u, 0x3F803F80u, 0x3F803F80u});
;               f32x4 sq = (f32x4){0.f, 0.f, 0.f, 0.f}, sb = sq;
; #pragma unroll
;               for (int kk2 = 0; kk2 < 2; ++kk2) {
;                   const bf16x8 fa = *(LAS const bf16x8*)(sc + 0 + (fr * 64 + kk2 * 32 + fq * 8) * 2), fu = *(LAS const bf16x8*)(sc + 2048 + (fr * 64 + kk2 * 32 + fq * 8) * 2);
;                   sq = __builtin_amdgcn_mfma_f32_16x16x32_bf16(fa, ones, sq, 0, 0, 0); sb = __builtin_amdgcn_mfma_f32_16x16x32_bf16(fu, ones, sb, 0, 0, 0);
;               }
;               if (fr == 0) { *(LAS f32x4*)(sl + SC_X + fq * 16) = sq; *(LAS f32x4*)(sl + SC_X + 64 + fq * 16) = sb; }
;     ...
;                 const float k = bf2f(kraw[t]), a = bf2f(araw[t]), r = bf2f(rraw[t]), ew = (float)eraw[t];
;                 const float kk = k * kkc * rsqrtf(fmaxf(*(LAS const float*)(sl + SC_X + t * 4), 1e-24f));
;                 const float kp = k * (1.f + (a - 1.f) * kac);
;                 const float at = -kk * W;
;                 W *= __expf(-ew);
	global_load_dwordx4 v[44:47], v8, s[26:27]
	global_load_dwordx4 v[48:51], v8, s[26:27] offset:16
	global_load_dwordx4 v[52:55], v8, s[36:37]
	global_load_dwordx4 v[56:59], v8, s[36:37] offset:16
	global_load_dwordx4 v[60:63], v8, s[38:39]
	global_load_dwordx4 v[64:67], v8, s[38:39] offset:16
	global_load_dwordx4 v[68:71], v8, s[46:47]
	global_load_dwordx4 v[72:75], v8, s[46:47] offset:16
	global_load_ushort v84, v9, s[60:61] offset:0
	global_load_ushort v85, v9, s[60:61] offset:1024
	global_load_ushort v86, v9, s[60:61] offset:2048
	global_load_ushort v87, v9, s[60:61] offset:3072
	v_add_u32_e32 v8, 0x18000, v8
	v_add_u32_e32 v9, 0x18000, v9
	s_nop 1
.Lsc_p_nopf:
	ds_read_b128 v[220:223], v42 offset:2304
	ds_read_b128 v[224:227], v42 offset:2320
	ds_read_b128 v[228:231], v42 offset:2048
	ds_read_b128 v[232:235], v42 offset:2064
	ds_read_b128 v[236:239], v42 offset:2560
	ds_read_b128 v[244:247], v42 offset:2576
	s_waitcnt lgkmcnt(0)
	v_add_f32_e32 v76, -1.0, v104
	v_add_f32_e32 v77, -1.0, v105
	v_add_f32_e32 v186, -1.0, v106
	v_add_f32_e32 v187, -1.0, v107
	v_pk_fma_f32 v[76:77], v[220:221], v[76:77], v[22:23]
	v_pk_fma_f32 v[186:187], v[222:223], v[186:187], v[22:23]
	v_pk_mul_f32 v[136:137], v[76:77], v[88:89]
	v_pk_mul_f32 v[138:139], v[186:187], v[90:91]
	v_pk_mul_f32 v[248:249], v[136:137], v[120:121]
	v_pk_mul_f32 v[194:195], v[138:139], v[122:123]
	v_add_f32_e32 v76, -1.0, v108
	v_add_f32_e32 v77, -1.0, v109
	v_add_f32_e32 v186, -1.0, v110
	v_add_f32_e32 v187, -1.0, v111
	v_pk_mul_f32 v[88:89], v[228:229], v[88:89]
	v_pk_mul_f32 v[248:249], v[236:237], v[248:249]
	v_pk_mul_f32 v[90:91], v[230:231], v[90:91]
	v_pk_mul_f32 v[194:195], v[238:239], v[194:195]
	v_pk_fma_f32 v[76:77], v[224:225], v[76:77], v[22:23]
	v_pk_fma_f32 v[186:187], v[226:227], v[186:187], v[22:23]
	v_pk_mul_f32 v[80:81], v[88:89], v[88:89]
	v_cvt_pk_bf16_f32 v204, v248, v249
	v_pk_mul_f32 v[188:189], v[90:91], v[90:91]
	v_cvt_pk_bf16_f32 v205, v194, v195
	v_pk_mul_f32 v[140:141], v[76:77], v[92:93]
	v_pk_mul_f32 v[142:143], v[186:187], v[94:95]
	v_cvt_pk_bf16_f32 v196, v80, v81
	v_cvt_pk_bf16_f32 v197, v188, v189
	v_pk_mul_f32 v[92:93], v[232:233], v[92:93]
	v_pk_mul_f32 v[248:249], v[140:141], v[124:125]
	v_pk_mul_f32 v[94:95], v[234:235], v[94:95]
	v_pk_mul_f32 v[194:195], v[142:143], v[126:127]
	ds_read_b128 v[220:223], v42 offset:2336
	ds_read_b128 v[224:227], v42 offset:2352
	v_pk_mul_f32 v[80:81], v[92:93], v[92:93]
	v_pk_mul_f32 v[248:249], v[244:245], v[248:249]
	v_pk_mul_f32 v[188:189], v[94:95], v[94:95]
	v_pk_mul_f32 v[194:195], v[246:247], v[194:195]
	ds_read_b128 v[228:231], v42 offset:2080
	ds_read_b128 v[232:235], v42 offset:2096
	v_cvt_pk_bf16_f32 v198, v80, v81
	v_cvt_pk_bf16_f32 v206, v248, v249
	v_cvt_pk_bf16_f32 v199, v188, v189
	v_cvt_pk_bf16_f32 v207, v194, v195
	ds_read_b128 v[236:239], v42 offset:2592
	ds_read_b128 v[244:247], v42 offset:2608
	s_waitcnt lgkmcnt(0)
	v_add_f32_e32 v76, -1.0, v112
	v_add_f32_e32 v77, -1.0, v113
	v_add_f32_e32 v186, -1.0, v114
	v_add_f32_e32 v187, -1.0, v115
	v_pk_fma_f32 v[76:77], v[220:221], v[76:77], v[22:23]
	v_pk_fma_f32 v[186:187], v[222:223], v[186:187], v[22:23]
	v_pk_mul_f32 v[144:145], v[76:77], v[96:97]
	v_pk_mul_f32 v[146:147], v[186:187], v[98:99]
	v_pk_mul_f32 v[248:249], v[144:145], v[128:129]
	v_pk_mul_f32 v[194:195], v[146:147], v[130:131]
	v_add_f32_e32 v76, -1.0, v116
	v_add_f32_e32 v77, -1.0, v117
	v_add_f32_e32 v186, -1.0, v118
	v_add_f32_e32 v187, -1.0, v119
	v_pk_mul_f32 v[96:97], v[228:229], v[96:97]
	v_pk_mul_f32 v[248:249], v[236:237], v[248:249]
	v_pk_mul_f32 v[98:99], v[230:231], v[98:99]
	v_pk_mul_f32 v[194:195], v[238:239], v[194:195]
	v_pk_fma_f32 v[76:77], v[224:225], v[76:77], v[22:23]
	v_pk_fma_f32 v[186:187], v[226:227], v[186:187], v[22:23]
	v_mfma_f32_16x16x32_bf16 v[168:171], v[28:31], v[196:199], 0
	v_mfma_f32_16x16x32_bf16 v[172:175], v[28:31], v[204:207], 0
	v_pk_mul_f32 v[80:81], v[96:97], v[96:97]
	v_cvt_pk_bf16_f32 v208, v248, v249
	v_pk_mul_f32 v[188:189], v[98:99], v[98:99]
	v_cvt_pk_bf16_f32 v209, v194, v195
	v_pk_mul_f32 v[148:149], v[76:77], v[100:101]
	v_pk_mul_f32 v[150:151], v[186:187], v[102:103]
	v_cvt_pk_bf16_f32 v200, v80, v81
	v_cvt_pk_bf16_f32 v201, v188, v189
	v_pk_mul_f32 v[100:101], v[232:233], v[100:101]
	v_pk_mul_f32 v[248:249], v[148:149], v[132:133]
	v_pk_mul_f32 v[102:103], v[234:235], v[102:103]
	v_pk_mul_f32 v[194:195], v[150:151], v[134:135]
	v_pk_mul_f32 v[80:81], v[100:101], v[100:101]
	v_pk_mul_f32 v[248:249], v[244:245], v[248:249]
	v_pk_mul_f32 v[188:189], v[102:103], v[102:103]
	v_pk_mul_f32 v[194:195], v[246:247], v[194:195]
	v_cvt_pk_bf16_f32 v202, v80, v81
	v_cvt_pk_bf16_f32 v210, v248, v249
	v_cvt_pk_bf16_f32 v203, v188, v189
	v_cvt_pk_bf16_f32 v211, v194, v195
	v_pk_mul_f32 v[152:153], v[152:153], v[24:25]
	v_pk_mul_f32 v[154:155], v[154:155], v[24:25]
	v_pk_mul_f32 v[156:157], v[156:157], v[24:25]
	v_pk_mul_f32 v[158:159], v[158:159], v[24:25]
	v_pk_mul_f32 v[160:161], v[160:161], v[24:25]
	v_pk_mul_f32 v[162:163], v[162:163], v[24:25]
	v_pk_mul_f32 v[164:165], v[164:165], v[24:25]
	v_pk_mul_f32 v[166:167], v[166:167], v[24:25]
	v_mfma_f32_16x16x32_bf16 v[168:171], v[28:31], v[200:203], v[168:171]
	v_mfma_f32_16x16x32_bf16 v[172:175], v[28:31], v[208:211], v[172:175]
	v_add_f32_dpp v152, v152, v152 row_shr:1 row_mask:0xf bank_mask:0xf bound_ctrl:1
	v_add_f32_dpp v153, v153, v153 row_shr:1 row_mask:0xf bank_mask:0xf bound_ctrl:1
	v_add_f32_dpp v154, v154, v154 row_shr:1 row_mask:0xf bank_mask:0xf bound_ctrl:1
	v_add_f32_dpp v155, v155, v155 row_shr:1 row_mask:0xf bank_mask:0xf bound_ctrl:1
; #define LAS __attribute__((address_space(3)))
; __device__ __forceinline__ float bf2f(bf16_t b) { return __uint_as_float(((unsigned)b) << 16); }
; __device__ __forceinline__ void phase_scan2(const Params& p, int l, LAS unsigned char* lds) {
;     ...
;               if (fr == 0) { *(LAS f32x4*)(sl + SC_X + fq * 16) = sq; *(LAS f32x4*)(sl + SC_X + 64 + fq * 16) = sb; }
;               asm volatile("s_waitcnt lgkmcnt(0)" ::: "memory");
;               if (rg == 0 && lane < 16) CB[(tok0 + (size_t)c * 16 + lane) * 8 + h] = *(LAS const float*)(sl + SC_X + 64 + lane * 4);
;               asm volatile("s_waitcnt lgkmcnt(0)" ::: "memory");
;             }
; #pragma unroll
;             for (int t = 0; t < 16; ++t) {
;                 const float k = bf2f(kraw[t]), a = bf2f(araw[t]), r = bf2f(rraw[t]), ew = (float)eraw[t];
;                 const float kk = k * kkc * rsqrtf(fmaxf(*(LAS const float*)(sl + SC_X + t * 4), 1e-24f));
;                 const float kp = k * (1.f + (a - 1.f) * kac);
;                 const float at = -kk * W;
;                 W *= __expf(-ew);
;                 const float rt = r * W, iw = __builtin_amdgcn_rcpf(W);
	v_add_f32_dpp v156, v156, v156 row_shr:1 row_mask:0xf bank_mask:0xf bound_ctrl:1
	v_add_f32_dpp v157, v157, v157 row_shr:1 row_mask:0xf bank_mask:0xf bound_ctrl:1
	v_add_f32_dpp v158, v158, v158 row_shr:1 row_mask:0xf bank_mask:0xf bound_ctrl:1
	v_add_f32_dpp v159, v159, v159 row_shr:1 row_mask:0xf bank_mask:0xf bound_ctrl:1
	v_add_f32_dpp v160, v160, v160 row_shr:1 row_mask:0xf bank_mask:0xf bound_ctrl:1
	v_add_f32_dpp v161, v161, v161 row_shr:1 row_mask:0xf bank_mask:0xf bound_ctrl:1
	v_add_f32_dpp v162, v162, v162 row_shr:1 row_mask:0xf bank_mask:0xf bound_ctrl:1
	v_add_f32_dpp v163, v163, v163 row_shr:1 row_mask:0xf bank_mask:0xf bound_ctrl:1
	v_add_f32_dpp v164, v164, v164 row_shr:1 row_mask:0xf bank_mask:0xf bound_ctrl:1
	v_add_f32_dpp v165, v165, v165 row_shr:1 row_mask:0xf bank_mask:0xf bound_ctrl:1
	v_add_f32_dpp v166, v166, v166 row_shr:1 row_mask:0xf bank_mask:0xf bound_ctrl:1
	v_add_f32_dpp v167, v167, v167 row_shr:1 row_mask:0xf bank_mask:0xf bound_ctrl:1
	v_add_f32_dpp v152, v152, v152 row_shr:2 row_mask:0xf bank_mask:0xf bound_ctrl:1
	v_add_f32_dpp v153, v153, v153 row_shr:2 row_mask:0xf bank_mask:0xf bound_ctrl:1
	v_add_f32_dpp v154, v154, v154 row_shr:2 row_mask:0xf bank_mask:0xf bound_ctrl:1
	v_add_f32_dpp v155, v155, v155 row_shr:2 row_mask:0xf bank_mask:0xf bound_ctrl:1
	v_add_f32_dpp v156, v156, v156 row_shr:2 row_mask:0xf bank_mask:0xf bound_ctrl:1
	v_add_f32_dpp v157, v157, v157 row_shr:2 row_mask:0xf bank_mask:0xf bound_ctrl:1
	v_add_f32_dpp v158, v158, v158 row_shr:2 row_mask:0xf bank_mask:0xf bound_ctrl:1
	v_add_f32_dpp v159, v159, v159 row_shr:2 row_mask:0xf bank_mask:0xf bound_ctrl:1
	v_add_f32_dpp v160, v160, v160 row_shr:2 row_mask:0xf bank_mask:0xf bound_ctrl:1
	v_add_f32_dpp v161, v161, v161 row_shr:2 row_mask:0xf bank_mask:0xf bound_ctrl:1
	v_add_f32_dpp v162, v162, v162 row_shr:2 row_mask:0xf bank_mask:0xf bound_ctrl:1
	v_add_f32_dpp v163, v163, v163 row_shr:2 row_mask:0xf bank_mask:0xf bound_ctrl:1
	v_add_f32_dpp v164, v164, v164 row_shr:2 row_mask:0xf bank_mask:0xf bound_ctrl:1
	v_add_f32_dpp v165, v165, v165 row_shr:2 row_mask:0xf bank_mask:0xf bound_ctrl:1
	v_add_f32_dpp v166, v166, v166 row_shr:2 row_mask:0xf bank_mask:0xf bound_ctrl:1
	v_add_f32_dpp v167, v167, v167 row_shr:2 row_mask:0xf bank_mask:0xf bound_ctrl:1
	v_add_f32_dpp v152, v152, v152 row_shr:4 row_mask:0xf bank_mask:0xf bound_ctrl:1
	v_add_f32_dpp v153, v153, v153 row_shr:4 row_mask:0xf bank_mask:0xf bound_ctrl:1
	v_add_f32_dpp v154, v154, v154 row_shr:4 row_mask:0xf bank_mask:0xf bound_ctrl:1
	v_add_f32_dpp v155, v155, v155 row_shr:4 row_mask:0xf bank_mask:0xf bound_ctrl:1
	v_add_f32_dpp v156, v156, v156 row_shr:4 row_mask:0xf bank_mask:0xf bound_ctrl:1
	v_add_f32_dpp v157, v157, v157 row_shr:4 row_mask:0xf bank_mask:0xf bound_ctrl:1
	v_add_f32_dpp v158, v158, v158 row_shr:4 row_mask:0xf bank_mask:0xf bound_ctrl:1
	v_add_f32_dpp v159, v159, v159 row_shr:4 row_mask:0xf bank_mask:0xf bound_ctrl:1
	v_add_f32_dpp v160, v160, v160 row_shr:4 row_mask:0xf bank_mask:0xf bound_ctrl:1
	v_add_f32_dpp v161, v161, v161 row_shr:4 row_mask:0xf bank_mask:0xf bound_ctrl:1
	v_add_f32_dpp v162, v162, v162 row_shr:4 row_mask:0xf bank_mask:0xf bound_ctrl:1
	v_add_f32_dpp v163, v163, v163 row_shr:4 row_mask:0xf bank_mask:0xf bound_ctrl:1
	v_add_f32_dpp v164, v164, v164 row_shr:4 row_mask:0xf bank_mask:0xf bound_ctrl:1
	v_add_f32_dpp v165, v165, v165 row_shr:4 row_mask:0xf bank_mask:0xf bound_ctrl:1
	v_add_f32_dpp v166, v166, v166 row_shr:4 row_mask:0xf bank_mask:0xf bound_ctrl:1
	v_add_f32_dpp v167, v167, v167 row_shr:4 row_mask:0xf bank_mask:0xf bound_ctrl:1
	v_add_f32_dpp v152, v152, v152 row_shr:8 row_mask:0xf bank_mask:0xf bound_ctrl:1
	v_add_f32_dpp v153, v153, v153 row_shr:8 row_mask:0xf bank_mask:0xf bound_ctrl:1
	v_add_f32_dpp v154, v154, v154 row_shr:8 row_mask:0xf bank_mask:0xf bound_ctrl:1
	v_add_f32_dpp v155, v155, v155 row_shr:8 row_mask:0xf bank_mask:0xf bound_ctrl:1
	v_add_f32_dpp v156, v156, v156 row_shr:8 row_mask:0xf bank_mask:0xf bound_ctrl:1
	v_add_f32_dpp v157, v157, v157 row_shr:8 row_mask:0xf bank_mask:0xf bound_ctrl:1
	v_add_f32_dpp v158, v158, v158 row_shr:8 row_mask:0xf bank_mask:0xf bound_ctrl:1
	v_add_f32_dpp v159, v159, v159 row_shr:8 row_mask:0xf bank_mask:0xf bound_ctrl:1
	v_add_f32_dpp v160, v160, v160 row_shr:8 row_mask:0xf bank_mask:0xf bound_ctrl:1
	v_add_f32_dpp v161, v161, v161 row_shr:8 row_mask:0xf bank_mask:0xf bound_ctrl:1
	v_add_f32_dpp v162, v162, v162 row_shr:8 row_mask:0xf bank_mask:0xf bound_ctrl:1
	v_add_f32_dpp v163, v163, v163 row_shr:8 row_mask:0xf bank_mask:0xf bound_ctrl:1
	v_add_f32_dpp v164, v164, v164 row_shr:8 row_mask:0xf bank_mask:0xf bound_ctrl:1
	v_add_f32_dpp v165, v165, v165 row_shr:8 row_mask:0xf bank_mask:0xf bound_ctrl:1
	v_add_f32_dpp v166, v166, v166 row_shr:8 row_mask:0xf bank_mask:0xf bound_ctrl:1
	v_add_f32_dpp v167, v167, v167 row_shr:8 row_mask:0xf bank_mask:0xf bound_ctrl:1
	v_exp_f32_e32 v196, v152
	v_exp_f32_e32 v197, v153
	v_exp_f32_e32 v198, v154
	v_exp_f32_e32 v199, v155
	v_exp_f32_e32 v200, v156
	v_exp_f32_e32 v201, v157
	v_exp_f32_e32 v202, v158
	v_exp_f32_e32 v203, v159
	v_exp_f32_e32 v204, v160
	v_exp_f32_e32 v205, v161
	v_exp_f32_e32 v206, v162
	v_exp_f32_e32 v207, v163
	v_exp_f32_e32 v208, v164
	v_exp_f32_e32 v209, v165
	v_exp_f32_e32 v210, v166
	v_exp_f32_e32 v211, v167
	v_max_f32_e32 v176, 0x179abe15, v168
	v_exp_f32_e64 v152, -v152
	v_rsq_f32_e32 v176, v176
	v_exp_f32_e64 v153, -v153
	v_exp_f32_e64 v154, -v154
	v_exp_f32_e64 v155, -v155
	v_exp_f32_e64 v156, -v156
	v_exp_f32_e64 v157, -v157
	v_exp_f32_e64 v158, -v158
	v_exp_f32_e64 v159, -v159
	v_exp_f32_e64 v160, -v160
	v_exp_f32_e64 v161, -v161
	v_exp_f32_e64 v162, -v162
	v_exp_f32_e64 v163, -v163
	v_exp_f32_e64 v164, -v164
	v_exp_f32_e64 v165, -v165
	v_exp_f32_e64 v166, -v166
	v_exp_f32_e64 v167, -v167
	s_cmp_lg_u32 s53, 0
	s_nop 0
	s_cbranch_scc1 .Lsc_p_nocb
	s_mov_b64 exec, 0xffff
	global_store_dword v10, v172, s[50:51]
	s_mov_b64 exec, -1
; #define LAS __attribute__((address_space(3)))
; __device__ __forceinline__ unsigned pk_bf16(float lo, float hi) { const f32x2_t f = {lo, hi}; return __builtin_bit_cast(unsigned, __builtin_convertvector(f, bf16x2_t)); }
; __device__ __forceinline__ float bf2f(bf16_t b) { return __uint_as_float(((unsigned)b) << 16); }
; __device__ __forceinline__ void phase_scan2(const Params& p, int l, LAS unsigned char* lds) {
;     ...
; #pragma unroll
;             for (int t = 0; t < 16; ++t) {
;                 const float k = bf2f(kraw[t]), a = bf2f(araw[t]), r = bf2f(rraw[t]), ew = (float)eraw[t];
;                 const float kk = k * kkc * rsqrtf(fmaxf(*(LAS const float*)(sl + SC_X + t * 4), 1e-24f));
;                 const float kp = k * (1.f + (a - 1.f) * kac);
;                 const float at = -kk * W;
;                 W *= __expf(-ew);
;                 const float rt = r * W, iw = __builtin_amdgcn_rcpf(W);
;                 const unsigned wbk = pk_bf16(kk * a * iw, kp * iw), war = pk_bf16(at, rt);
;                 const bf16_t bh = (bf16_t)(wbk & 0xffffu), kh = (bf16_t)(wbk >> 16), ah = (bf16_t)(war & 0xffffu), rh = (bf16_t)(war >> 16);
;                 *(LAS bf16_t*)(sl + SC_AT + ((m * 16 + t) * 32 + pidx) * 2) = ah;
;                 *(LAS bf16_t*)(sl + SC_RT + ((m * 16 + t) * 32 + pidx) * 2) = rh;
;                 *(LAS bf16_t*)(sl + SC_BBT + (j * SC_BS + t) * 2) = bh;
;                 *(LAS bf16_t*)(sl + SC_KBT + (j * SC_BS + t) * 2) = kh;
;                 *(LAS bf16_t*)(sc + 0 + ((m * 16 + t) * 32 + pidx) * 2) = bh;
;                 *(LAS bf16_t*)(sc + 2048 + ((m * 16 + t) * 32 + pidx) * 2) = kh;
.Lsc_p_nocb:
	v_mov_b32_dpp v76, v196 row_shr:1 row_mask:0xf bank_mask:0xf bound_ctrl:1
	v_mov_b32_dpp v77, v197 row_shr:1 row_mask:0xf bank_mask:0xf bound_ctrl:1
	v_mov_b32_dpp v186, v198 row_shr:1 row_mask:0xf bank_mask:0xf bound_ctrl:1
	v_mov_b32_dpp v187, v199 row_shr:1 row_mask:0xf bank_mask:0xf bound_ctrl:1
	v_pk_mul_f32 v[88:89], v[88:89], v[176:177] op_sel_hi:[1,0]
	v_max_f32_e32 v76, v76, v21
	v_max_f32_e32 v77, v77, v21
	v_pk_mul_f32 v[90:91], v[90:91], v[176:177] op_sel_hi:[1,0]
	v_max_f32_e32 v186, v186, v21
	v_max_f32_e32 v187, v187, v21
	v_pk_mul_f32 v[76:77], v[88:89], v[76:77] neg_lo:[1,0] neg_hi:[1,0]
	v_pk_mul_f32 v[186:187], v[90:91], v[186:187] neg_lo:[1,0] neg_hi:[1,0]
	v_cvt_pk_bf16_f32 v168, v76, v77
	v_cvt_pk_bf16_f32 v169, v186, v187
	v_mov_b32_dpp v76, v200 row_shr:1 row_mask:0xf bank_mask:0xf bound_ctrl:1
	v_mov_b32_dpp v77, v201 row_shr:1 row_mask:0xf bank_mask:0xf bound_ctrl:1
	v_mov_b32_dpp v186, v202 row_shr:1 row_mask:0xf bank_mask:0xf bound_ctrl:1
	v_mov_b32_dpp v187, v203 row_shr:1 row_mask:0xf bank_mask:0xf bound_ctrl:1
	v_pk_mul_f32 v[92:93], v[92:93], v[176:177] op_sel_hi:[1,0]
	v_max_f32_e32 v76, v76, v21
	v_max_f32_e32 v77, v77, v21
	v_pk_mul_f32 v[94:95], v[94:95], v[176:177] op_sel_hi:[1,0]
	v_max_f32_e32 v186, v186, v21
	v_max_f32_e32 v187, v187, v21
	v_pk_mul_f32 v[76:77], v[92:93], v[76:77] neg_lo:[1,0] neg_hi:[1,0]
	v_pk_mul_f32 v[186:187], v[94:95], v[186:187] neg_lo:[1,0] neg_hi:[1,0]
	v_cvt_pk_bf16_f32 v170, v76, v77
	v_cvt_pk_bf16_f32 v171, v186, v187
	v_mov_b32_dpp v76, v204 row_shr:1 row_mask:0xf bank_mask:0xf bound_ctrl:1
	v_mov_b32_dpp v77, v205 row_shr:1 row_mask:0xf bank_mask:0xf bound_ctrl:1
	v_mov_b32_dpp v186, v206 row_shr:1 row_mask:0xf bank_mask:0xf bound_ctrl:1
	v_mov_b32_dpp v187, v207 row_shr:1 row_mask:0xf bank_mask:0xf bound_ctrl:1
	v_pk_mul_f32 v[80:81], v[120:121], v[196:197]
	v_pk_mul_f32 v[104:105], v[88:89], v[104:105]
	v_pk_mul_f32 v[188:189], v[122:123], v[198:199]
	v_pk_mul_f32 v[106:107], v[90:91], v[106:107]
	v_pk_mul_f32 v[96:97], v[96:97], v[176:177] op_sel_hi:[1,0]
	v_max_f32_e32 v76, v76, v21
	v_max_f32_e32 v77, v77, v21
	v_pk_mul_f32 v[98:99], v[98:99], v[176:177] op_sel_hi:[1,0]
	v_max_f32_e32 v186, v186, v21
	v_max_f32_e32 v187, v187, v21
	v_pk_mul_f32 v[248:249], v[104:105], v[152:153]
	v_cvt_pk_bf16_f32 v220, v80, v81
	v_pk_mul_f32 v[194:195], v[106:107], v[154:155]
	v_cvt_pk_bf16_f32 v221, v188, v189
	v_pk_mul_f32 v[76:77], v[96:97], v[76:77] neg_lo:[1,0] neg_hi:[1,0]
	v_pk_mul_f32 v[186:187], v[98:99], v[186:187] neg_lo:[1,0] neg_hi:[1,0]
	v_pk_mul_f32 v[250:251], v[136:137], v[152:153]
	v_cvt_pk_bf16_f32 v228, v248, v249
	v_pk_mul_f32 v[212:213], v[138:139], v[154:155]
	v_cvt_pk_bf16_f32 v229, v194, v195
	v_pk_mul_f32 v[80:81], v[124:125], v[200:201]
	v_pk_mul_f32 v[108:109], v[92:93], v[108:109]
	v_pk_mul_f32 v[188:189], v[126:127], v[202:203]
	v_pk_mul_f32 v[110:111], v[94:95], v[110:111]
	v_cvt_pk_bf16_f32 v172, v76, v77
	v_cvt_pk_bf16_f32 v173, v186, v187
	v_cvt_pk_bf16_f32 v236, v250, v251
	v_cvt_pk_bf16_f32 v237, v212, v213
	v_pk_mul_f32 v[248:249], v[108:109], v[156:157]
	v_cvt_pk_bf16_f32 v222, v80, v81
	v_pk_mul_f32 v[194:195], v[110:111], v[158:159]
	v_cvt_pk_bf16_f32 v223, v188, v189
	v_mov_b32_dpp v76, v208 row_shr:1 row_mask:0xf bank_mask:0xf bound_ctrl:1
	v_mov_b32_dpp v77, v209 row_shr:1 row_mask:0xf bank_mask:0xf bound_ctrl:1
	v_mov_b32_dpp v186, v210 row_shr:1 row_mask:0xf bank_mask:0xf bound_ctrl:1
	v_mov_b32_dpp v187, v211 row_shr:1 row_mask:0xf bank_mask:0xf bound_ctrl:1
	v_pk_mul_f32 v[250:251], v[140:141], v[156:157]
	v_cvt_pk_bf16_f32 v230, v248, v249
	v_pk_mul_f32 v[212:213], v[142:143], v[158:159]
	v_cvt_pk_bf16_f32 v231, v194, v195
	v_pk_mul_f32 v[80:81], v[128:129], v[204:205]
	v_pk_mul_f32 v[112:113], v[96:97], v[112:113]
	v_pk_mul_f32 v[188:189], v[130:131], v[206:207]
	v_pk_mul_f32 v[114:115], v[98:99], v[114:115]
	v_pk_mul_f32 v[100:101], v[100:101], v[176:177] op_sel_hi:[1,0]
	v_max_f32_e32 v76, v76, v21
	v_max_f32_e32 v77, v77, v21
	v_pk_mul_f32 v[102:103], v[102:103], v[176:177] op_sel_hi:[1,0]
	v_max_f32_e32 v186, v186, v21
	v_max_f32_e32 v187, v187, v21
	v_cvt_pk_bf16_f32 v238, v250, v251
	v_cvt_pk_bf16_f32 v239, v212, v213
	v_pk_mul_f32 v[248:249], v[112:113], v[160:161]
	v_cvt_pk_bf16_f32 v224, v80, v81
	v_pk_mul_f32 v[194:195], v[114:115], v[162:163]
	v_cvt_pk_bf16_f32 v225, v188, v189
	v_pk_mul_f32 v[76:77], v[100:101], v[76:77] neg_lo:[1,0] neg_hi:[1,0]
	v_pk_mul_f32 v[186:187], v[102:103], v[186:187] neg_lo:[1,0] neg_hi:[1,0]
	v_pk_mul_f32 v[250:251], v[144:145], v[160:161]
	v_cvt_pk_bf16_f32 v232, v248, v249
	v_pk_mul_f32 v[212:213], v[146:147], v[162:163]
	v_cvt_pk_bf16_f32 v233, v194, v195
	v_pk_mul_f32 v[80:81], v[132:133], v[208:209]
	v_pk_mul_f32 v[116:117], v[100:101], v[116:117]
	v_cvt_pk_bf16_f32 v174, v76, v77
	v_pk_mul_f32 v[188:189], v[134:135], v[210:211]
	v_pk_mul_f32 v[118:119], v[102:103], v[118:119]
	v_cvt_pk_bf16_f32 v175, v186, v187
	ds_write_b128 v17, v[168:171] offset:0
; #define LAS __attribute__((address_space(3)))
; __device__ __forceinline__ void phase_scan2(const Params& p, int l, LAS unsigned char* lds) {
;     ...
;                 *(LAS bf16_t*)(sl + SC_AT + ((m * 16 + t) * 32 + pidx) * 2) = ah;
;                 *(LAS bf16_t*)(sl + SC_RT + ((m * 16 + t) * 32 + pidx) * 2) = rh;
;                 *(LAS bf16_t*)(sl + SC_BBT + (j * SC_BS + t) * 2) = bh;
;                 *(LAS bf16_t*)(sl + SC_KBT + (j * SC_BS + t) * 2) = kh;
;                 *(LAS bf16_t*)(sc + 0 + ((m * 16 + t) * 32 + pidx) * 2) = bh;
;                 *(LAS bf16_t*)(sc + 2048 + ((m * 16 + t) * 32 + pidx) * 2) = kh;
;             }
;             *(LAS float*)(sl + SC_WC + j * 4) = W;
; #pragma unroll
;             for (int q = 0; q < 4; ++q) *(LAS bf16_t*)(sl + SC_VP + (fr * 16 + 4 * fq + q) * 2) = vraw[q];
;             if (cnext >= 0) pload(cnext);
;             asm volatile("s_waitcnt lgkmcnt(0)" ::: "memory");
;             f32x4 AB = (f32x4){0.f, 0.f, 0.f, 0.f}, AKm = AB, RBm = AB, RKm = AB;
; #pragma unroll
;             for (int kk2 = 0; kk2 < 2; ++kk2) {
;                 const int fo = ((kk2 * 16 + fr) * 32 + fq * 8) * 2;
;                 const bf16x8 fa = *(LAS const bf16x8*)(sl + SC_AT + fo), fr_ = *(LAS const bf16x8*)(sl + SC_RT + fo);
;                 const bf16x8 fb = *(LAS const bf16x8*)(sc + 0 + fo), fk = *(LAS const bf16x8*)(sc + 2048 + fo);
;                 AB = __builtin_amdgcn_mfma_f32_16x16x32_bf16(fa, fb, AB, 0, 0, 0); AKm = __builtin_amdgcn_mfma_f32_16x16x32_bf16(fa, fk, AKm, 0, 0, 0);
;                 RBm = __builtin_amdgcn_mfma_f32_16x16x32_bf16(fr_, fb, RBm, 0, 0, 0); RKm = __builtin_amdgcn_mfma_f32_16x16x32_bf16(fr_, fk, RKm, 0, 0, 0);
;             }
; #pragma unroll
;             for (int r = 0; r < 4; ++r) { const int t = 4 * fq + r; const bool lo = fr < t, le = fr <= t;
;                 AB[r] = lo ? AB[r] : 0.f; AKm[r] = lo ? AKm[r] : 0.f; RBm[r] = le ? RBm[r] : 0.f; RKm[r] = le ? RKm[r] : 0.f; }
;             asm volatile("s_waitcnt lgkmcnt(0)" ::: "memory");
;             st_mat(sl + SC_AK, nullptr, nullptr, nullptr, AKm, fr, fq);
;             st_mat(sl + SC_RB, nullptr, nullptr, nullptr, RBm, fr, fq);
;             st_mat(sl + SC_RK, nullptr, nullptr, nullptr, RKm, fr, fq);
	v_cvt_pk_bf16_f32 v244, v250, v251
	v_cvt_pk_bf16_f32 v245, v212, v213
	v_pk_mul_f32 v[248:249], v[116:117], v[164:165]
	v_cvt_pk_bf16_f32 v226, v80, v81
	v_pk_mul_f32 v[194:195], v[118:119], v[166:167]
	v_cvt_pk_bf16_f32 v227, v188, v189
	ds_write_b128 v18, v[172:175] offset:0
	ds_write_b128 v17, v[220:223] offset:2048
	v_pk_mul_f32 v[250:251], v[148:149], v[164:165]
	v_cvt_pk_bf16_f32 v234, v248, v249
	v_pk_mul_f32 v[212:213], v[150:151], v[166:167]
	v_cvt_pk_bf16_f32 v235, v194, v195
	ds_write_b128 v18, v[224:227] offset:2048
	ds_write_b128 v17, v[228:231] offset:4096
	v_cvt_pk_bf16_f32 v246, v250, v251
	v_cvt_pk_bf16_f32 v247, v212, v213
	ds_write_b128 v18, v[232:235] offset:4096
	ds_write_b128 v17, v[236:239] offset:6144
	ds_write_b128 v18, v[244:247] offset:6144
	s_mov_b32 exec_lo, 0x80008000
	s_mov_b32 exec_hi, 0x80008000
	ds_write_b128 v20, v[196:199] offset:0
	ds_write_b128 v20, v[200:203] offset:16
	ds_write_b128 v20, v[204:207] offset:32
	ds_write_b128 v20, v[208:211] offset:48
	s_mov_b64 exec, -1
	v_mfma_f32_16x16x32_bf16 v[92:95], v[168:171], v[236:239], 0
	v_mfma_f32_16x16x32_bf16 v[96:99], v[220:223], v[228:231], 0
	v_mfma_f32_16x16x32_bf16 v[100:103], v[220:223], v[236:239], 0
	v_mfma_f32_16x16x32_bf16 v[88:91], v[168:171], v[228:231], 0
	v_mfma_f32_16x16x32_bf16 v[92:95], v[172:175], v[244:247], v[92:95]
	v_mfma_f32_16x16x32_bf16 v[96:99], v[224:227], v[232:235], v[96:99]
	v_mfma_f32_16x16x32_bf16 v[100:103], v[224:227], v[244:247], v[100:103]
	v_mfma_f32_16x16x32_bf16 v[88:91], v[172:175], v[232:235], v[88:91]
	s_nop 4
	v_mul_f32_e32 v92, v34, v92
	v_mul_f32_e32 v93, v35, v93
	v_mul_f32_e32 v94, v36, v94
	v_mul_f32_e32 v95, v37, v95
	v_cvt_pk_bf16_f32 v76, v92, v93
	v_cvt_pk_bf16_f32 v77, v94, v95
	v_mul_f32_e32 v96, v38, v96
	v_mul_f32_e32 v97, v39, v97
	v_mul_f32_e32 v98, v40, v98
	v_mul_f32_e32 v99, v41, v99
	ds_write_b64 v19, v[76:77] offset:8192
	v_cvt_pk_bf16_f32 v76, v96, v97
	v_cvt_pk_bf16_f32 v77, v98, v99
	v_mul_f32_e32 v100, v38, v100
	v_mul_f32_e32 v101, v39, v101
	v_mul_f32_e32 v102, v40, v102
	v_mul_f32_e32 v103, v41, v103
	ds_write_b64 v19, v[76:77] offset:9216
	v_mul_f32_e32 v88, v34, v88
	v_mul_f32_e32 v89, v35, v89
	v_mul_f32_e32 v90, v36, v90
	v_mul_f32_e32 v91, v37, v91
	v_cvt_pk_bf16_f32 v76, v100, v101
	v_cvt_pk_bf16_f32 v77, v102, v103
	v_add_f32_e32 v248, v26, v88
	ds_write_b64 v19, v[76:77] offset:9728
	v_add_f32_e32 v249, v27, v89
	v_add_f32_e32 v250, v32, v90
	v_add_f32_e32 v251, v33, v91
	v_cvt_pk_bf16_f32 v76, v88, v89
	v_cvt_pk_bf16_f32 v77, v90, v91
	v_cvt_pk_bf16_f32 v80, v248, v249
	v_cvt_pk_bf16_f32 v81, v250, v251
	ds_write_b64 v15, v[76:77] offset:0
	ds_write_b64 v15, v[80:81] offset:512
	ds_read_b64_tr_b16 v[112:113], v14 offset:0
	ds_read_b64 v[114:115], v15 offset:0
	s_waitcnt lgkmcnt(0)
	v_mfma_f32_16x16x16_bf16 v[104:107], v[112:113], v[114:115], 0
	s_nop 7
	v_add_f32_e32 v248, v26, v104
	v_add_f32_e32 v249, v27, v105
	v_add_f32_e32 v250, v32, v106
	v_add_f32_e32 v251, v33, v107
	v_cvt_pk_bf16_f32 v76, v104, v105
	v_cvt_pk_bf16_f32 v77, v106, v107
	v_cvt_pk_bf16_f32 v80, v248, v249
	v_cvt_pk_bf16_f32 v81, v250, v251
	ds_write_b64 v15, v[76:77] offset:1024
	ds_write_b64 v15, v[80:81] offset:1536
	ds_read_b64_tr_b16 v[112:113], v14 offset:1024
	ds_read_b64 v[114:115], v15 offset:1024
	ds_read_b64_tr_b16 v[116:117], v14 offset:512
	ds_read_b64 v[118:119], v15 offset:1536
	s_waitcnt lgkmcnt(2)
	v_mfma_f32_16x16x16_bf16 v[104:107], v[112:113], v[114:115], 0
	s_waitcnt lgkmcnt(0)
	v_mfma_f32_16x16x16_bf16 v[108:111], v[116:117], v[118:119], 0
	s_nop 5
	v_cvt_pk_bf16_f32 v76, v104, v105
	v_cvt_pk_bf16_f32 v77, v106, v107
	v_add_f32_e32 v248, v26, v104
	v_add_f32_e32 v249, v27, v105
	v_add_f32_e32 v250, v32, v106
	v_add_f32_e32 v251, v33, v107
	ds_write_b64 v15, v[76:77] offset:0
	v_cvt_pk_bf16_f32 v80, v248, v249
	v_cvt_pk_bf16_f32 v81, v250, v251
	v_cvt_pk_bf16_f32 v76, v108, v109
	v_cvt_pk_bf16_f32 v77, v110, v111
	ds_write_b64 v15, v[80:81] offset:512
	ds_write_b64 v15, v[76:77] offset:1024
	ds_read_b64_tr_b16 v[112:113], v14 offset:0
	ds_read_b64 v[114:115], v15 offset:0
	ds_read_b64_tr_b16 v[116:117], v14 offset:1024
	ds_read_b64 v[118:119], v15 offset:512
	s_waitcnt lgkmcnt(2)
	v_mfma_f32_16x16x16_bf16 v[104:107], v[112:113], v[114:115], 0
	s_waitcnt lgkmcnt(0)
	v_mfma_f32_16x16x16_bf16 v[108:111], v[116:117], v[118:119], 0
	s_nop 5
	v_add_f32_e32 v248, v26, v104
	v_add_f32_e32 v249, v27, v105
	v_add_f32_e32 v250, v32, v106
	v_add_f32_e32 v251, v33, v107
	v_cvt_pk_bf16_f32 v80, v248, v249
	v_cvt_pk_bf16_f32 v81, v250, v251
	ds_write_b64 v15, v[80:81] offset:1536
	v_cvt_pk_bf16_f32 v76, v108, v109
	v_cvt_pk_bf16_f32 v77, v110, v111
	ds_write_b64 v15, v[76:77] offset:0
	ds_read_b64_tr_b16 v[112:113], v14 offset:0
	ds_read_b64 v[114:115], v15 offset:1536
	s_waitcnt lgkmcnt(0)
	v_mfma_f32_16x16x16_bf16 v[104:107], v[112:113], v[114:115], 0
	s_nop 7
	v_cvt_pk_bf16_f32 v76, v104, v105
	v_cvt_pk_bf16_f32 v77, v106, v107
	ds_write_b64 v19, v[76:77] offset:8704
	s_nop 0

; #define LAS __attribute__((address_space(3)))
; __device__ __forceinline__ unsigned pk_bf16(float lo, float hi) { const f32x2_t f = {lo, hi}; return __builtin_bit_cast(unsigned, __builtin_convertvector(f, bf16x2_t)); }
; __device__ __forceinline__ void phase_scan2(const Params& p, int l, LAS unsigned char* lds) {
;     ...
;         f32x4 ST[4];
; #pragma unroll
;         for (int jt = 0; jt < 4; ++jt) ST[jt] = (f32x4){0.f, 0.f, 0.f, 0.f};
;         auto consume = [&](int c, LAS const unsigned char* sl) {
;             const bf16x8 s0 = __builtin_bit_cast(bf16x8, (u32x4){pk_bf16(ST[0][0], ST[0][1]), pk_bf16(ST[0][2], ST[0][3]), pk_bf16(ST[1][0], ST[1][1]), pk_bf16(ST[1][2], ST[1][3])});
;             const bf16x8 s1 = __builtin_bit_cast(bf16x8, (u32x4){pk_bf16(ST[2][0], ST[2][1]), pk_bf16(ST[2][2], ST[2][3]), pk_bf16(ST[3][0], ST[3][1]), pk_bf16(ST[3][2], ST[3][3])});
;             const bf16x8 at0 = *(LAS const bf16x8*)(sl + SC_AT + (fr * 32 + fq * 8) * 2), at1 = *(LAS const bf16x8*)(sl + SC_AT + ((16 + fr) * 32 + fq * 8) * 2);
;             const bf16x8 rt0 = *(LAS const bf16x8*)(sl + SC_RT + (fr * 32 + fq * 8) * 2), rt1 = *(LAS const bf16x8*)(sl + SC_RT + ((16 + fr) * 32 + fq * 8) * 2);
;             const int mo = (fr * 16 + 4 * fq) * 2;
;             const bf16x8 vf = frag4(sl + SC_VP + mo), akf = frag4(sl + SC_AK + mo), xf = frag4(sl + SC_X + mo), rbf = frag4(sl + SC_RB + mo), rkf = frag4(sl + SC_RK + mo);
;             const f32x4 z = (f32x4){0.f, 0.f, 0.f, 0.f};
.Lsc_consumer:
	v_and_b32_e32 v4, 7, v1
	v_and_b32_e32 v5, 3, v1
	v_xor_b32_e32 v4, v4, v2
	s_mul_i32 s0, s54, 4096
	v_lshlrev_b32_e32 v4, 4, v4
	s_lshl_b32 s0, s0, 10
	v_lshl_add_u32 v113, v1, 7, v4
	v_lshrrev_b32_e32 v4, 2, v1
	s_lshl_b32 s14, s52, 7
	v_lshl_add_u32 v4, v2, 2, v4
	s_lshl_b32 s15, s53, 5
	v_and_b32_e32 v115, 7, v4
	s_add_u32 s0, s0, s14
	v_xor_b32_e32 v115, v115, v5
	v_lshlrev_b32_e32 v114, 5, v2
	v_lshlrev_b32_e32 v115, 4, v115
	v_lshlrev_b32_e32 v116, 12, v2
	v_lshl_add_u32 v115, v4, 7, v115
	s_add_u32 s0, s0, s15
	v_add_u32_e32 v115, 4096, v115
	s_add_u32 s0, s0, 0x5000000
	v_mov_b32_e32 v8, 0
	v_mov_b32_e32 v9, 0
	v_mov_b32_e32 v10, 0
	v_mov_b32_e32 v11, 0
	v_mov_b32_e32 v16, 0
	v_mov_b32_e32 v17, 0
	v_mov_b32_e32 v18, 0
	v_mov_b32_e32 v19, 0
	v_mov_b32_e32 v20, 0
	v_mov_b32_e32 v21, 0
	v_mov_b32_e32 v22, 0
	v_mov_b32_e32 v23, 0
	v_mov_b32_e32 v24, 0
	v_mov_b32_e32 v25, 0
	v_mov_b32_e32 v26, 0
	v_mov_b32_e32 v27, 0
	v_xor_b32_e32 v119, 64, v113
	v_add_u32_e32 v114, 10752, v114
	v_xor_b32_e32 v120, 64, v115
	v_lshl_add_u32 v116, v1, 1, v116
	s_add_u32 s48, s74, s0
	s_addc_u32 s49, s75, 0
	s_mov_b32 s42, 0
	s_mov_b32 s58, 0
	s_mov_b32 s56, 0
	s_branch .Lsc_c_bar

; __device__ __forceinline__ void phase_scan2(const Params& p, int l, LAS unsigned char* lds) {
;     ...
;         auto consume = [&](int c, LAS const unsigned char* sl) {
;             const bf16x8 s0 = __builtin_bit_cast(bf16x8, (u32x4){pk_bf16(ST[0][0], ST[0][1]), pk_bf16(ST[0][2], ST[0][3]), pk_bf16(ST[1][0], ST[1][1]), pk_bf16(ST[1][2], ST[1][3])});
;             const bf16x8 s1 = __builtin_bit_cast(bf16x8, (u32x4){pk_bf16(ST[2][0], ST[2][1]), pk_bf16(ST[2][2], ST[2][3]), pk_bf16(ST[3][0], ST[3][1]), pk_bf16(ST[3][2], ST[3][3])});
;             const bf16x8 at0 = *(LAS const bf16x8*)(sl + SC_AT + (fr * 32 + fq * 8) * 2), at1 = *(LAS const bf16x8*)(sl + SC_AT + ((16 + fr) * 32 + fq * 8) * 2);
;             const bf16x8 rt0 = *(LAS const bf16x8*)(sl + SC_RT + (fr * 32 + fq * 8) * 2), rt1 = *(LAS const bf16x8*)(sl + SC_RT + ((16 + fr) * 32 + fq * 8) * 2);
;             const int mo = (fr * 16 + 4 * fq) * 2;
;             const bf16x8 vf = frag4(sl + SC_VP + mo), akf = frag4(sl + SC_AK + mo), xf = frag4(sl + SC_X + mo), rbf = frag4(sl + SC_RB + mo), rkf = frag4(sl + SC_RK + mo);
;             const f32x4 z = (f32x4){0.f, 0.f, 0.f, 0.f};
;             f32x4 g = __builtin_amdgcn_mfma_f32_16x16x32_bf16(at0, s0, z, 0, 0, 0);
;             g = __builtin_amdgcn_mfma_f32_16x16x32_bf16(at1, s1, g, 0, 0, 0);
;             g = __builtin_amdgcn_mfma_f32_16x16x32_bf16(akf, vf, g, 0, 0, 0);
;             const f32x4 sa = __builtin_amdgcn_mfma_f32_16x16x32_bf16(xf, cfrag(g), z, 0, 0, 0);
;             const bf16x8 saf = cfrag(sa);
;             f32x4 y = __builtin_amdgcn_mfma_f32_16x16x32_bf16(rt0, s0, z, 0, 0, 0);
;             y = __builtin_amdgcn_mfma_f32_16x16x32_bf16(rt1, s1, y, 0, 0, 0);
;             y = __builtin_amdgcn_mfma_f32_16x16x32_bf16(rbf, saf, y, 0, 0, 0);
;             y = __builtin_amdgcn_mfma_f32_16x16x32_bf16(rkf, vf, y, 0, 0, 0);
; #pragma unroll
;             for (int jt = 0; jt < 4; ++jt) {
;                 const f32x4 wc = *(LAS const f32x4*)(sl + SC_WC + (16 * jt + 4 * fq) * 4);
;                 const bf16x8 bb = frag4(sl + SC_BBT + ((16 * jt + fr) * SC_BS + 4 * fq) * 2), kb = frag4(sl + SC_KBT + ((16 * jt + fr) * SC_BS + 4 * fq) * 2);
;                 f32x4 acc = ST[jt];
;                 acc = __builtin_amdgcn_mfma_f32_16x16x32_bf16(bb, saf, acc, 0, 0, 0);
;                 acc = __builtin_amdgcn_mfma_f32_16x16x32_bf16(kb, vf, acc, 0, 0, 0);
.Lsc_c_chunk:
	s_cmp_ge_u32 s58, 256
	s_cbranch_scc1 .Lsc_c_next
	v_add_u32_e32 v13, s57, v113
	v_add_u32_e32 v121, s57, v119
	ds_read_b128 v[36:39], v13 offset:0
	ds_read_b128 v[44:47], v13 offset:2048
	v_add_u32_e32 v78, s57, v6
	ds_read_b128 v[40:43], v121 offset:0
	v_add_u32_e32 v112, s57, v115
	ds_read_b128 v[48:51], v121 offset:2048
	ds_read_b64 v[14:15], v78 offset:10240
	v_add_u32_e32 v122, s57, v120
	ds_read_b64_tr_b16 v[88:89], v112 offset:2048
	ds_read_b64_tr_b16 v[90:91], v112 offset:2056
	v_add_u32_e32 v118, s57, v7
	ds_read_b64_tr_b16 v[92:93], v122 offset:2048
	ds_read_b64_tr_b16 v[94:95], v122 offset:2056
	ds_read_b64_tr_b16 v[52:53], v118 offset:8192
	ds_read_b64_tr_b16 v[58:59], v118 offset:9728
	v_add_u32_e32 v82, s57, v114
	ds_read_b64_tr_b16 v[54:55], v118 offset:8704
	v_cvt_pk_bf16_f32 v28, v8, v9
	v_cvt_pk_bf16_f32 v29, v10, v11
	v_cvt_pk_bf16_f32 v30, v16, v17
	v_cvt_pk_bf16_f32 v31, v18, v19
	v_cvt_pk_bf16_f32 v32, v20, v21
	v_cvt_pk_bf16_f32 v33, v22, v23
	v_cvt_pk_bf16_f32 v34, v24, v25
	v_cvt_pk_bf16_f32 v35, v26, v27
	ds_read_b64_tr_b16 v[56:57], v118 offset:9216
	s_waitcnt lgkmcnt(12)
	v_mfma_f32_16x16x32_bf16 v[96:99], v[36:39], v[28:31], 0
	s_waitcnt lgkmcnt(11)
	v_mfma_f32_16x16x32_bf16 v[104:107], v[44:47], v[28:31], 0
	ds_read_b64_tr_b16 v[76:77], v112 offset:0
	ds_read_b64_tr_b16 v[80:81], v112 offset:8
	ds_read_b64_tr_b16 v[84:85], v122 offset:0
	ds_read_b64_tr_b16 v[86:87], v122 offset:8
	s_waitcnt lgkmcnt(14)
	v_mfma_f32_16x16x32_bf16 v[96:99], v[40:43], v[32:35], v[96:99]
	s_waitcnt lgkmcnt(13)
	v_mfma_f32_16x16x32_bf16 v[104:107], v[48:51], v[32:35], v[104:107]
	s_waitcnt lgkmcnt(8)
	v_mfma_f32_16x16x16_bf16 v[8:11], v[88:89], v[14:15], v[8:11]
	v_mfma_f32_16x16x16_bf16 v[16:19], v[90:91], v[14:15], v[16:19]
	v_mfma_f32_16x16x16_bf16 v[20:23], v[92:93], v[14:15], v[20:23]
	v_mfma_f32_16x16x16_bf16 v[24:27], v[94:95], v[14:15], v[24:27]
	ds_read_b128 v[60:63], v82 offset:0
	ds_read_b128 v[64:67], v82 offset:16
	ds_read_b128 v[68:71], v82 offset:128
	ds_read_b128 v[72:75], v82 offset:144
	s_waitcnt lgkmcnt(10)
	v_mfma_f32_16x16x16_bf16 v[96:99], v[52:53], v[14:15], v[96:99]
	v_mfma_f32_16x16x16_bf16 v[104:107], v[58:59], v[14:15], v[104:107]
	s_nop 6
	v_cvt_pk_bf16_f32 v108, v96, v97
	v_cvt_pk_bf16_f32 v109, v98, v99
	s_waitcnt lgkmcnt(9)
	s_nop 0
	v_mfma_f32_16x16x16_bf16 v[100:103], v[54:55], v[108:109], 0
	s_nop 7
	v_cvt_pk_bf16_f32 v110, v100, v101
	v_cvt_pk_bf16_f32 v111, v102, v103
	s_waitcnt lgkmcnt(4)
	s_nop 0
	v_mfma_f32_16x16x16_bf16 v[104:107], v[56:57], v[110:111], v[104:107]
	v_mfma_f32_16x16x16_bf16 v[8:11], v[76:77], v[110:111], v[8:11]
	v_mfma_f32_16x16x16_bf16 v[16:19], v[80:81], v[110:111], v[16:19]
	v_mfma_f32_16x16x16_bf16 v[20:23], v[84:85], v[110:111], v[20:23]
	v_mfma_f32_16x16x16_bf16 v[24:27], v[86:87], v[110:111], v[24:27]
	s_nop 3
	v_cvt_pk_bf16_f32 v117, v104, v104
	global_store_short v116, v117, s[48:49] offset:0
	v_cvt_pk_bf16_f32 v117, v105, v105
	global_store_short v116, v117, s[48:49] offset:1024
	v_cvt_pk_bf16_f32 v117, v106, v106
	global_store_short v116, v117, s[48:49] offset:2048
	v_cvt_pk_bf16_f32 v117, v107, v107
	global_store_short v116, v117, s[48:49] offset:3072
	s_waitcnt lgkmcnt(0)
	v_pk_mul_f32 v[8:9], v[8:9], v[60:61]
	v_pk_mul_f32 v[10:11], v[10:11], v[62:63]
	v_pk_mul_f32 v[16:17], v[16:17], v[64:65]
	v_pk_mul_f32 v[18:19], v[18:19], v[66:67]
	v_pk_mul_f32 v[20:21], v[20:21], v[68:69]
	v_pk_mul_f32 v[22:23], v[22:23], v[70:71]
	v_pk_mul_f32 v[24:25], v[24:25], v[72:73]
	v_pk_mul_f32 v[26:27], v[26:27], v[74:75]
	s_nop 1

; __device__ __forceinline__ void phase_scan2(const Params& p, int l, LAS unsigned char* lds) {
;     ...
;         }
;         __syncthreads();
;     }
.Lsc_job_end:
	s_setprio 0
	s_add_u32 s13, s13, s62
	s_cmp_lt_u32 s13, 256
	s_cbranch_scc1 .Lsc_job
	s_waitcnt vmcnt(0) lgkmcnt(0)
